# K-loops: s_setprio 0 issued after the segment-closing barrier instead of before it (one fewer instruction between last MFMA and barrier)
# baseline (speedup 1.0000x reference)
.LBB0_207:
	ds_read_b128 v[156:159], v152
	ds_read_b128 v[160:163], v152 offset:1024
	ds_read_b128 v[164:167], v152 offset:2048
	ds_read_b128 v[168:171], v152 offset:3072
	ds_read_b128 v[172:175], v153
	ds_read_b128 v[176:179], v153 offset:1024
	ds_read_b128 v[180:183], v153 offset:2048
	ds_read_b128 v[184:187], v153 offset:3072
	s_add_u32 s36, s0, 0xfffe0080
	s_addc_u32 s37, s1, -1
	s_cmp_eq_u32 s62, 4
	s_cselect_b32 s39, s25, s37
	s_cselect_b32 s38, s27, s36
	s_cselect_b32 s37, s29, s61
	s_cselect_b32 s36, s28, s60
	v_lshl_add_u64 v[146:147], s[0:1], 0, v[138:139]
	s_add_i32 m0, s35, 0xc000
	ds_read_b128 v[188:191], v154
	ds_read_b128 v[192:195], v154 offset:1024
	ds_read_b128 v[196:199], v154 offset:2048
	ds_read_b128 v[200:203], v154 offset:3072
	ds_read_b128 v[204:207], v154 offset:4096
	ds_read_b128 v[208:211], v154 offset:5120
	ds_read_b128 v[212:215], v154 offset:6144
	ds_read_b128 v[216:219], v154 offset:7168
	global_load_lds_dwordx4 v[146:147], off
	v_lshl_add_u64 v[146:147], s[0:1], 0, v[140:141]
	s_add_i32 m0, s35, 0xe000
	s_nop 0
	global_load_lds_dwordx4 v[146:147], off
	s_waitcnt vmcnt(8)
	s_waitcnt lgkmcnt(0)
	s_barrier
	s_setprio 1
	s_waitcnt lgkmcnt(0)
	v_mfma_f32_16x16x32_bf16 v[126:129], v[156:159], v[188:191], v[126:129]
	v_mfma_f32_16x16x32_bf16 v[122:125], v[164:167], v[188:191], v[122:125]
	v_mfma_f32_16x16x32_bf16 v[118:121], v[156:159], v[196:199], v[118:121]
	v_mfma_f32_16x16x32_bf16 v[110:113], v[164:167], v[196:199], v[110:113]
	v_mfma_f32_16x16x32_bf16 v[102:105], v[156:159], v[204:207], v[102:105]
	v_mfma_f32_16x16x32_bf16 v[94:97], v[164:167], v[204:207], v[94:97]
	v_mfma_f32_16x16x32_bf16 v[86:89], v[156:159], v[212:215], v[86:89]
	v_mfma_f32_16x16x32_bf16 v[78:81], v[164:167], v[212:215], v[78:81]
	v_mfma_f32_16x16x32_bf16 v[126:129], v[160:163], v[192:195], v[126:129]
	v_mfma_f32_16x16x32_bf16 v[122:125], v[168:171], v[192:195], v[122:125]
	v_mfma_f32_16x16x32_bf16 v[118:121], v[160:163], v[200:203], v[118:121]
	v_mfma_f32_16x16x32_bf16 v[110:113], v[168:171], v[200:203], v[110:113]
	v_mfma_f32_16x16x32_bf16 v[102:105], v[160:163], v[208:211], v[102:105]
	v_mfma_f32_16x16x32_bf16 v[94:97], v[168:171], v[208:211], v[94:97]
	v_mfma_f32_16x16x32_bf16 v[86:89], v[160:163], v[216:219], v[86:89]
	v_mfma_f32_16x16x32_bf16 v[78:81], v[168:171], v[216:219], v[78:81]
	s_setprio 0
	s_setprio 1
	v_mfma_f32_16x16x32_bf16 v[114:117], v[172:175], v[188:191], v[114:117]
	v_mfma_f32_16x16x32_bf16 v[106:109], v[180:183], v[188:191], v[106:109]
	v_mfma_f32_16x16x32_bf16 v[98:101], v[172:175], v[196:199], v[98:101]
	v_mfma_f32_16x16x32_bf16 v[90:93], v[180:183], v[196:199], v[90:93]
	v_mfma_f32_16x16x32_bf16 v[82:85], v[172:175], v[204:207], v[82:85]
	v_mfma_f32_16x16x32_bf16 v[74:77], v[180:183], v[204:207], v[74:77]
	v_mfma_f32_16x16x32_bf16 v[70:73], v[172:175], v[212:215], v[70:73]
	v_mfma_f32_16x16x32_bf16 v[66:69], v[180:183], v[212:215], v[66:69]
	v_mfma_f32_16x16x32_bf16 v[114:117], v[176:179], v[192:195], v[114:117]
	v_mfma_f32_16x16x32_bf16 v[106:109], v[184:187], v[192:195], v[106:109]
	v_mfma_f32_16x16x32_bf16 v[98:101], v[176:179], v[200:203], v[98:101]
	v_mfma_f32_16x16x32_bf16 v[90:93], v[184:187], v[200:203], v[90:93]
	v_mfma_f32_16x16x32_bf16 v[82:85], v[176:179], v[208:211], v[82:85]
	v_mfma_f32_16x16x32_bf16 v[74:77], v[184:187], v[208:211], v[74:77]
	v_mfma_f32_16x16x32_bf16 v[70:73], v[176:179], v[216:219], v[70:73]
	v_mfma_f32_16x16x32_bf16 v[66:69], v[184:187], v[216:219], v[66:69]
	s_barrier
	s_setprio 0
	s_add_i32 s63, s53, s43
	v_lshl_add_u64 v[146:147], s[36:37], 0, v[132:133]
	s_mov_b32 m0, s63
	ds_read_b128 v[188:191], v154 offset:16384
	ds_read_b128 v[192:195], v154 offset:17408
	ds_read_b128 v[196:199], v154 offset:18432
	ds_read_b128 v[200:203], v154 offset:19456
	ds_read_b128 v[204:207], v154 offset:20480
	ds_read_b128 v[208:211], v154 offset:21504
	ds_read_b128 v[212:215], v154 offset:22528
	ds_read_b128 v[216:219], v154 offset:23552
	global_load_lds_dwordx4 v[146:147], off
	s_add_i32 m0, s63, 0x2000
	s_add_u32 s64, s36, 0x80000
	v_lshl_add_u64 v[220:221], s[36:37], 0, v[136:137]
	s_addc_u32 s65, s37, 0
	s_add_i32 s63, s54, s43
	global_load_lds_dwordx4 v[220:221], off
	v_lshl_add_u64 v[222:223], s[64:65], 0, v[132:133]
	s_mov_b32 m0, s63
	v_lshl_add_u64 v[224:225], s[38:39], 0, v[134:135]
	global_load_lds_dwordx4 v[222:223], off
	v_lshl_add_u64 v[222:223], s[64:65], 0, v[136:137]
	s_add_i32 m0, s63, 0x2000
	s_nop 0
	global_load_lds_dwordx4 v[222:223], off
	v_lshl_add_u64 v[222:223], s[38:39], 0, v[130:131]
	s_mov_b32 m0, s35
	s_nop 0
	global_load_lds_dwordx4 v[222:223], off
	s_mov_b32 m0, s46
	s_nop 0
	global_load_lds_dwordx4 v[224:225], off
	s_waitcnt vmcnt(8)
	s_waitcnt lgkmcnt(0)
	s_barrier
	s_setprio 1
	s_waitcnt lgkmcnt(0)
	v_mfma_f32_16x16x32_bf16 v[62:65], v[156:159], v[188:191], v[62:65]
	v_mfma_f32_16x16x32_bf16 v[58:61], v[164:167], v[188:191], v[58:61]
	v_mfma_f32_16x16x32_bf16 v[54:57], v[156:159], v[196:199], v[54:57]
	v_mfma_f32_16x16x32_bf16 v[46:49], v[164:167], v[196:199], v[46:49]
	v_mfma_f32_16x16x32_bf16 v[38:41], v[156:159], v[204:207], v[38:41]
	v_mfma_f32_16x16x32_bf16 v[30:33], v[164:167], v[204:207], v[30:33]
	v_mfma_f32_16x16x32_bf16 v[22:25], v[156:159], v[212:215], v[22:25]
	v_mfma_f32_16x16x32_bf16 v[14:17], v[164:167], v[212:215], v[14:17]
	v_mfma_f32_16x16x32_bf16 v[62:65], v[160:163], v[192:195], v[62:65]
	v_mfma_f32_16x16x32_bf16 v[58:61], v[168:171], v[192:195], v[58:61]
	v_mfma_f32_16x16x32_bf16 v[54:57], v[160:163], v[200:203], v[54:57]
	v_mfma_f32_16x16x32_bf16 v[46:49], v[168:171], v[200:203], v[46:49]
	v_mfma_f32_16x16x32_bf16 v[38:41], v[160:163], v[208:211], v[38:41]
	v_mfma_f32_16x16x32_bf16 v[30:33], v[168:171], v[208:211], v[30:33]
	v_mfma_f32_16x16x32_bf16 v[22:25], v[160:163], v[216:219], v[22:25]
	v_mfma_f32_16x16x32_bf16 v[14:17], v[168:171], v[216:219], v[14:17]
	s_setprio 0
	s_setprio 1
	v_mfma_f32_16x16x32_bf16 v[50:53], v[172:175], v[188:191], v[50:53]
	v_mfma_f32_16x16x32_bf16 v[42:45], v[180:183], v[188:191], v[42:45]
	v_mfma_f32_16x16x32_bf16 v[34:37], v[172:175], v[196:199], v[34:37]
	v_mfma_f32_16x16x32_bf16 v[26:29], v[180:183], v[196:199], v[26:29]
	v_mfma_f32_16x16x32_bf16 v[18:21], v[172:175], v[204:207], v[18:21]
	v_mfma_f32_16x16x32_bf16 v[10:13], v[180:183], v[204:207], v[10:13]
	v_mfma_f32_16x16x32_bf16 v[6:9], v[172:175], v[212:215], v[6:9]
	v_mfma_f32_16x16x32_bf16 v[2:5], v[180:183], v[212:215], v[2:5]
	v_mfma_f32_16x16x32_bf16 v[50:53], v[176:179], v[192:195], v[50:53]
	v_mfma_f32_16x16x32_bf16 v[42:45], v[184:187], v[192:195], v[42:45]
	v_mfma_f32_16x16x32_bf16 v[34:37], v[176:179], v[200:203], v[34:37]
	v_mfma_f32_16x16x32_bf16 v[26:29], v[184:187], v[200:203], v[26:29]
	v_mfma_f32_16x16x32_bf16 v[18:21], v[176:179], v[208:211], v[18:21]
	v_mfma_f32_16x16x32_bf16 v[10:13], v[184:187], v[208:211], v[10:13]
	v_mfma_f32_16x16x32_bf16 v[6:9], v[176:179], v[216:219], v[6:9]
	v_mfma_f32_16x16x32_bf16 v[2:5], v[184:187], v[216:219], v[2:5]
	s_barrier
	s_setprio 0
	s_add_i32 s63, 0, 0x18000
	v_add_u32_e32 v155, s63, v150
	s_add_i32 s64, 0, 0x1c000
	ds_read_b128 v[156:159], v155
	ds_read_b128 v[160:163], v155 offset:1024
	ds_read_b128 v[164:167], v155 offset:2048
	ds_read_b128 v[168:171], v155 offset:3072
	v_add_u32_e32 v155, s64, v150
	ds_read_b128 v[172:175], v155
	ds_read_b128 v[176:179], v155 offset:1024
	ds_read_b128 v[180:183], v155 offset:2048
	ds_read_b128 v[184:187], v155 offset:3072
	s_add_u32 s38, s38, 0x20000
	s_addc_u32 s39, s39, 0
	s_mov_b32 m0, s47
	v_lshl_add_u64 v[226:227], s[38:39], 0, v[130:131]
	ds_read_b128 v[188:191], v154 offset:32768
	ds_read_b128 v[192:195], v154 offset:33792
	ds_read_b128 v[196:199], v154 offset:34816
	ds_read_b128 v[200:203], v154 offset:35840
	ds_read_b128 v[204:207], v154 offset:36864
	ds_read_b128 v[208:211], v154 offset:37888
	ds_read_b128 v[212:215], v154 offset:38912
	ds_read_b128 v[216:219], v154 offset:39936
	global_load_lds_dwordx4 v[226:227], off
	v_lshl_add_u64 v[226:227], s[38:39], 0, v[134:135]
	s_mov_b32 m0, s48
	s_nop 0
	global_load_lds_dwordx4 v[226:227], off
	s_waitcnt vmcnt(8)
	s_waitcnt lgkmcnt(0)
	s_barrier
	s_setprio 1
	s_waitcnt lgkmcnt(0)
	v_mfma_f32_16x16x32_bf16 v[126:129], v[156:159], v[188:191], v[126:129]
	v_mfma_f32_16x16x32_bf16 v[122:125], v[164:167], v[188:191], v[122:125]
	v_mfma_f32_16x16x32_bf16 v[118:121], v[156:159], v[196:199], v[118:121]
	v_mfma_f32_16x16x32_bf16 v[110:113], v[164:167], v[196:199], v[110:113]
	v_mfma_f32_16x16x32_bf16 v[102:105], v[156:159], v[204:207], v[102:105]
	v_mfma_f32_16x16x32_bf16 v[94:97], v[164:167], v[204:207], v[94:97]
	v_mfma_f32_16x16x32_bf16 v[86:89], v[156:159], v[212:215], v[86:89]
	v_mfma_f32_16x16x32_bf16 v[78:81], v[164:167], v[212:215], v[78:81]
	v_mfma_f32_16x16x32_bf16 v[126:129], v[160:163], v[192:195], v[126:129]
	v_mfma_f32_16x16x32_bf16 v[122:125], v[168:171], v[192:195], v[122:125]
	v_mfma_f32_16x16x32_bf16 v[118:121], v[160:163], v[200:203], v[118:121]
	v_mfma_f32_16x16x32_bf16 v[110:113], v[168:171], v[200:203], v[110:113]
	v_mfma_f32_16x16x32_bf16 v[102:105], v[160:163], v[208:211], v[102:105]
	v_mfma_f32_16x16x32_bf16 v[94:97], v[168:171], v[208:211], v[94:97]
	v_mfma_f32_16x16x32_bf16 v[86:89], v[160:163], v[216:219], v[86:89]
	v_mfma_f32_16x16x32_bf16 v[78:81], v[168:171], v[216:219], v[78:81]
	s_setprio 0
	s_setprio 1
	v_mfma_f32_16x16x32_bf16 v[114:117], v[172:175], v[188:191], v[114:117]
	v_mfma_f32_16x16x32_bf16 v[106:109], v[180:183], v[188:191], v[106:109]
	v_mfma_f32_16x16x32_bf16 v[98:101], v[172:175], v[196:199], v[98:101]
	v_mfma_f32_16x16x32_bf16 v[90:93], v[180:183], v[196:199], v[90:93]
	v_mfma_f32_16x16x32_bf16 v[82:85], v[172:175], v[204:207], v[82:85]
	v_mfma_f32_16x16x32_bf16 v[74:77], v[180:183], v[204:207], v[74:77]
	v_mfma_f32_16x16x32_bf16 v[70:73], v[172:175], v[212:215], v[70:73]
	v_mfma_f32_16x16x32_bf16 v[66:69], v[180:183], v[212:215], v[66:69]
	v_mfma_f32_16x16x32_bf16 v[114:117], v[176:179], v[192:195], v[114:117]
	v_mfma_f32_16x16x32_bf16 v[106:109], v[184:187], v[192:195], v[106:109]
	v_mfma_f32_16x16x32_bf16 v[98:101], v[176:179], v[200:203], v[98:101]
	v_mfma_f32_16x16x32_bf16 v[90:93], v[184:187], v[200:203], v[90:93]
	v_mfma_f32_16x16x32_bf16 v[82:85], v[176:179], v[208:211], v[82:85]
	v_mfma_f32_16x16x32_bf16 v[74:77], v[184:187], v[208:211], v[74:77]
	v_mfma_f32_16x16x32_bf16 v[70:73], v[176:179], v[216:219], v[70:73]
	v_mfma_f32_16x16x32_bf16 v[66:69], v[184:187], v[216:219], v[66:69]
	s_barrier
	s_setprio 0
	s_add_i32 s38, s63, s43
	v_lshl_add_u64 v[146:147], v[146:147], 0, s[8:9]
	s_mov_b32 m0, s38
	ds_read_b128 v[188:191], v154 offset:49152
	ds_read_b128 v[192:195], v154 offset:50176
	ds_read_b128 v[196:199], v154 offset:51200
	ds_read_b128 v[200:203], v154 offset:52224
	ds_read_b128 v[204:207], v154 offset:53248
	ds_read_b128 v[208:211], v154 offset:54272
	ds_read_b128 v[212:215], v154 offset:55296
	ds_read_b128 v[216:219], v154 offset:56320
	global_load_lds_dwordx4 v[146:147], off
	s_add_i32 m0, s38, 0x2000
	s_add_u32 s36, s36, 0x80080
	v_lshl_add_u64 v[146:147], v[220:221], 0, s[8:9]
	s_addc_u32 s37, s37, 0
	s_add_i32 s38, s64, s43
	global_load_lds_dwordx4 v[146:147], off
	v_lshl_add_u64 v[146:147], s[36:37], 0, v[132:133]
	s_mov_b32 m0, s38
	s_nop 0
	global_load_lds_dwordx4 v[146:147], off
	v_lshl_add_u64 v[146:147], s[36:37], 0, v[136:137]
	s_add_i32 m0, s38, 0x2000
	s_nop 0
	global_load_lds_dwordx4 v[146:147], off
	v_lshl_add_u64 v[146:147], v[222:223], 0, s[8:9]
	s_mov_b32 m0, s50
	s_nop 0
	global_load_lds_dwordx4 v[146:147], off
	v_lshl_add_u64 v[146:147], v[224:225], 0, s[8:9]
	s_mov_b32 m0, s51
	s_nop 0
	global_load_lds_dwordx4 v[146:147], off
	s_waitcnt vmcnt(8)
	s_waitcnt lgkmcnt(0)
	s_barrier
	s_setprio 1
	s_waitcnt lgkmcnt(0)
	v_mfma_f32_16x16x32_bf16 v[62:65], v[156:159], v[188:191], v[62:65]
	v_mfma_f32_16x16x32_bf16 v[58:61], v[164:167], v[188:191], v[58:61]
	v_mfma_f32_16x16x32_bf16 v[54:57], v[156:159], v[196:199], v[54:57]
	v_mfma_f32_16x16x32_bf16 v[46:49], v[164:167], v[196:199], v[46:49]
	v_mfma_f32_16x16x32_bf16 v[38:41], v[156:159], v[204:207], v[38:41]
	v_mfma_f32_16x16x32_bf16 v[30:33], v[164:167], v[204:207], v[30:33]
	v_mfma_f32_16x16x32_bf16 v[22:25], v[156:159], v[212:215], v[22:25]
	v_mfma_f32_16x16x32_bf16 v[14:17], v[164:167], v[212:215], v[14:17]
	v_mfma_f32_16x16x32_bf16 v[62:65], v[160:163], v[192:195], v[62:65]
	v_mfma_f32_16x16x32_bf16 v[58:61], v[168:171], v[192:195], v[58:61]
	v_mfma_f32_16x16x32_bf16 v[54:57], v[160:163], v[200:203], v[54:57]
	v_mfma_f32_16x16x32_bf16 v[46:49], v[168:171], v[200:203], v[46:49]
	v_mfma_f32_16x16x32_bf16 v[38:41], v[160:163], v[208:211], v[38:41]
	v_mfma_f32_16x16x32_bf16 v[30:33], v[168:171], v[208:211], v[30:33]
	v_mfma_f32_16x16x32_bf16 v[22:25], v[160:163], v[216:219], v[22:25]
	v_mfma_f32_16x16x32_bf16 v[14:17], v[168:171], v[216:219], v[14:17]
	s_setprio 0
	s_setprio 1
	v_mfma_f32_16x16x32_bf16 v[50:53], v[172:175], v[188:191], v[50:53]
	v_mfma_f32_16x16x32_bf16 v[42:45], v[180:183], v[188:191], v[42:45]
	v_mfma_f32_16x16x32_bf16 v[34:37], v[172:175], v[196:199], v[34:37]
	v_mfma_f32_16x16x32_bf16 v[26:29], v[180:183], v[196:199], v[26:29]
	v_mfma_f32_16x16x32_bf16 v[18:21], v[172:175], v[204:207], v[18:21]
	v_mfma_f32_16x16x32_bf16 v[10:13], v[180:183], v[204:207], v[10:13]
	v_mfma_f32_16x16x32_bf16 v[6:9], v[172:175], v[212:215], v[6:9]
	v_mfma_f32_16x16x32_bf16 v[2:5], v[180:183], v[212:215], v[2:5]
	v_mfma_f32_16x16x32_bf16 v[50:53], v[176:179], v[192:195], v[50:53]
	v_mfma_f32_16x16x32_bf16 v[42:45], v[184:187], v[192:195], v[42:45]
	v_mfma_f32_16x16x32_bf16 v[34:37], v[176:179], v[200:203], v[34:37]
	v_mfma_f32_16x16x32_bf16 v[26:29], v[184:187], v[200:203], v[26:29]
	v_mfma_f32_16x16x32_bf16 v[18:21], v[176:179], v[208:211], v[18:21]
	v_mfma_f32_16x16x32_bf16 v[10:13], v[184:187], v[208:211], v[10:13]
	v_mfma_f32_16x16x32_bf16 v[6:9], v[176:179], v[216:219], v[6:9]
	v_mfma_f32_16x16x32_bf16 v[2:5], v[184:187], v[216:219], v[2:5]
	s_barrier
	s_setprio 0
	s_add_i32 s62, s62, 2
	s_add_u32 s0, s0, 0x100
	s_addc_u32 s1, s1, 0
	s_add_u32 s60, s60, 0x100
	s_addc_u32 s61, s61, 0
	s_cmp_gt_u32 s62, 5
	s_cbranch_scc0 .LBB0_207
	s_and_b64 vcc, exec, s[10:11]
	s_cbranch_vccz .LBB0_210
	s_barrier

.LBB0_290:
	s_add_u32 s12, s60, s10
	s_addc_u32 s13, s61, s11
	s_add_u32 s12, s12, 0x100
	s_addc_u32 s13, s13, 0
	s_add_u32 s97, s28, s10
	s_addc_u32 vcc_lo, s29, s11
	s_add_i32 vcc_hi, 0, 0x10000
	s_cmpk_eq_i32 s10, 0xf00
	s_cselect_b32 s41, s63, s13
	s_cselect_b32 s40, s94, s12
	v_add_u32_e32 v154, vcc_hi, v169
	s_cselect_b32 s13, s67, vcc_lo
	s_cselect_b32 s12, s95, s97
	s_add_i32 s97, 0, 0x14000
	ds_read_b128 v[146:149], v154
	ds_read_b128 v[150:153], v154 offset:1024
	ds_read_b128 v[164:167], v154 offset:2048
	ds_read_b128 v[172:175], v154 offset:3072
	v_add_u32_e32 v154, s97, v169
	ds_read_b128 v[176:179], v154
	ds_read_b128 v[180:183], v154 offset:1024
	ds_read_b128 v[184:187], v154 offset:2048
	ds_read_b128 v[188:191], v154 offset:3072
	v_lshl_add_u64 v[196:197], v[142:143], 0, s[10:11]
	s_add_i32 m0, s81, 0xc000
	ds_read_b128 v[200:203], v171
	ds_read_b128 v[204:207], v171 offset:1024
	ds_read_b128 v[208:211], v171 offset:2048
	ds_read_b128 v[212:215], v171 offset:3072
	ds_read_b128 v[216:219], v171 offset:4096
	ds_read_b128 v[220:223], v171 offset:5120
	ds_read_b128 v[224:227], v171 offset:6144
	ds_read_b128 v[228:231], v171 offset:7168
	global_load_lds_dwordx4 v[196:197], off
	v_lshl_add_u64 v[196:197], v[144:145], 0, s[10:11]
	s_add_i32 m0, s81, 0xe000
	s_nop 0
	global_load_lds_dwordx4 v[196:197], off
	s_waitcnt vmcnt(8)
	s_waitcnt lgkmcnt(0)
	s_barrier
	s_setprio 1
	s_waitcnt lgkmcnt(0)
	v_mfma_f32_16x16x32_bf16 v[126:129], v[146:149], v[200:203], v[126:129]
	v_mfma_f32_16x16x32_bf16 v[122:125], v[164:167], v[200:203], v[122:125]
	v_mfma_f32_16x16x32_bf16 v[118:121], v[146:149], v[208:211], v[118:121]
	v_mfma_f32_16x16x32_bf16 v[114:117], v[164:167], v[208:211], v[114:117]
	v_mfma_f32_16x16x32_bf16 v[110:113], v[146:149], v[216:219], v[110:113]
	v_mfma_f32_16x16x32_bf16 v[106:109], v[164:167], v[216:219], v[106:109]
	v_mfma_f32_16x16x32_bf16 v[102:105], v[146:149], v[224:227], v[102:105]
	v_mfma_f32_16x16x32_bf16 v[98:101], v[164:167], v[224:227], v[98:101]
	v_mfma_f32_16x16x32_bf16 v[126:129], v[150:153], v[204:207], v[126:129]
	v_mfma_f32_16x16x32_bf16 v[122:125], v[172:175], v[204:207], v[122:125]
	v_mfma_f32_16x16x32_bf16 v[118:121], v[150:153], v[212:215], v[118:121]
	v_mfma_f32_16x16x32_bf16 v[114:117], v[172:175], v[212:215], v[114:117]
	v_mfma_f32_16x16x32_bf16 v[110:113], v[150:153], v[220:223], v[110:113]
	v_mfma_f32_16x16x32_bf16 v[106:109], v[172:175], v[220:223], v[106:109]
	v_mfma_f32_16x16x32_bf16 v[102:105], v[150:153], v[228:231], v[102:105]
	v_mfma_f32_16x16x32_bf16 v[98:101], v[172:175], v[228:231], v[98:101]
	s_setprio 0
	s_setprio 1
	v_mfma_f32_16x16x32_bf16 v[94:97], v[176:179], v[200:203], v[94:97]
	v_mfma_f32_16x16x32_bf16 v[90:93], v[184:187], v[200:203], v[90:93]
	v_mfma_f32_16x16x32_bf16 v[86:89], v[176:179], v[208:211], v[86:89]
	v_mfma_f32_16x16x32_bf16 v[82:85], v[184:187], v[208:211], v[82:85]
	v_mfma_f32_16x16x32_bf16 v[78:81], v[176:179], v[216:219], v[78:81]
	v_mfma_f32_16x16x32_bf16 v[74:77], v[184:187], v[216:219], v[74:77]
	v_mfma_f32_16x16x32_bf16 v[70:73], v[176:179], v[224:227], v[70:73]
	v_mfma_f32_16x16x32_bf16 v[66:69], v[184:187], v[224:227], v[66:69]
	v_mfma_f32_16x16x32_bf16 v[94:97], v[180:183], v[204:207], v[94:97]
	v_mfma_f32_16x16x32_bf16 v[90:93], v[188:191], v[204:207], v[90:93]
	v_mfma_f32_16x16x32_bf16 v[86:89], v[180:183], v[212:215], v[86:89]
	v_mfma_f32_16x16x32_bf16 v[82:85], v[188:191], v[212:215], v[82:85]
	v_mfma_f32_16x16x32_bf16 v[78:81], v[180:183], v[220:223], v[78:81]
	v_mfma_f32_16x16x32_bf16 v[74:77], v[188:191], v[220:223], v[74:77]
	v_mfma_f32_16x16x32_bf16 v[70:73], v[180:183], v[228:231], v[70:73]
	v_mfma_f32_16x16x32_bf16 v[66:69], v[188:191], v[228:231], v[66:69]
	s_barrier
	s_setprio 0
	s_add_i32 vcc_lo, vcc_hi, s80
	v_lshl_add_u64 v[196:197], s[12:13], 0, v[132:133]
	s_mov_b32 m0, vcc_lo
	ds_read_b128 v[200:203], v171 offset:16384
	ds_read_b128 v[204:207], v171 offset:17408
	ds_read_b128 v[208:211], v171 offset:18432
	ds_read_b128 v[212:215], v171 offset:19456
	ds_read_b128 v[216:219], v171 offset:20480
	ds_read_b128 v[220:223], v171 offset:21504
	ds_read_b128 v[224:227], v171 offset:22528
	ds_read_b128 v[228:231], v171 offset:23552
	global_load_lds_dwordx4 v[196:197], off
	s_add_i32 m0, vcc_lo, 0x2000
	s_add_u32 vcc_lo, s12, 0x80000
	v_lshl_add_u64 v[232:233], s[12:13], 0, v[136:137]
	s_addc_u32 vcc_hi, s13, 0
	s_add_i32 s97, s97, s80
	global_load_lds_dwordx4 v[232:233], off
	v_lshl_add_u64 v[234:235], vcc, 0, v[132:133]
	s_mov_b32 m0, s97
	v_lshl_add_u64 v[236:237], s[40:41], 0, v[134:135]
	global_load_lds_dwordx4 v[234:235], off
	v_lshl_add_u64 v[234:235], vcc, 0, v[136:137]
	s_add_i32 m0, s97, 0x2000
	s_nop 0
	global_load_lds_dwordx4 v[234:235], off
	v_lshl_add_u64 v[234:235], s[40:41], 0, v[130:131]
	s_mov_b32 m0, s81
	s_nop 0
	global_load_lds_dwordx4 v[234:235], off
	s_mov_b32 m0, s82
	s_nop 0
	global_load_lds_dwordx4 v[236:237], off
	s_waitcnt vmcnt(8)
	s_waitcnt lgkmcnt(0)
	s_barrier
	s_setprio 1
	s_waitcnt lgkmcnt(0)
	v_mfma_f32_16x16x32_bf16 v[62:65], v[146:149], v[200:203], v[62:65]
	v_mfma_f32_16x16x32_bf16 v[58:61], v[164:167], v[200:203], v[58:61]
	v_mfma_f32_16x16x32_bf16 v[54:57], v[146:149], v[208:211], v[54:57]
	v_mfma_f32_16x16x32_bf16 v[50:53], v[164:167], v[208:211], v[50:53]
	v_mfma_f32_16x16x32_bf16 v[46:49], v[146:149], v[216:219], v[46:49]
	v_mfma_f32_16x16x32_bf16 v[42:45], v[164:167], v[216:219], v[42:45]
	v_mfma_f32_16x16x32_bf16 v[38:41], v[146:149], v[224:227], v[38:41]
	v_mfma_f32_16x16x32_bf16 v[34:37], v[164:167], v[224:227], v[34:37]
	v_mfma_f32_16x16x32_bf16 v[62:65], v[150:153], v[204:207], v[62:65]
	v_mfma_f32_16x16x32_bf16 v[58:61], v[172:175], v[204:207], v[58:61]
	v_mfma_f32_16x16x32_bf16 v[54:57], v[150:153], v[212:215], v[54:57]
	v_mfma_f32_16x16x32_bf16 v[50:53], v[172:175], v[212:215], v[50:53]
	v_mfma_f32_16x16x32_bf16 v[46:49], v[150:153], v[220:223], v[46:49]
	v_mfma_f32_16x16x32_bf16 v[42:45], v[172:175], v[220:223], v[42:45]
	v_mfma_f32_16x16x32_bf16 v[38:41], v[150:153], v[228:231], v[38:41]
	v_mfma_f32_16x16x32_bf16 v[34:37], v[172:175], v[228:231], v[34:37]
	s_setprio 0
	s_setprio 1
	v_mfma_f32_16x16x32_bf16 v[30:33], v[176:179], v[200:203], v[30:33]
	v_mfma_f32_16x16x32_bf16 v[26:29], v[184:187], v[200:203], v[26:29]
	v_mfma_f32_16x16x32_bf16 v[22:25], v[176:179], v[208:211], v[22:25]
	v_mfma_f32_16x16x32_bf16 v[18:21], v[184:187], v[208:211], v[18:21]
	v_mfma_f32_16x16x32_bf16 v[14:17], v[176:179], v[216:219], v[14:17]
	v_mfma_f32_16x16x32_bf16 v[10:13], v[184:187], v[216:219], v[10:13]
	v_mfma_f32_16x16x32_bf16 v[6:9], v[176:179], v[224:227], v[6:9]
	v_mfma_f32_16x16x32_bf16 v[2:5], v[184:187], v[224:227], v[2:5]
	v_mfma_f32_16x16x32_bf16 v[30:33], v[180:183], v[204:207], v[30:33]
	v_mfma_f32_16x16x32_bf16 v[26:29], v[188:191], v[204:207], v[26:29]
	v_mfma_f32_16x16x32_bf16 v[22:25], v[180:183], v[212:215], v[22:25]
	v_mfma_f32_16x16x32_bf16 v[18:21], v[188:191], v[212:215], v[18:21]
	v_mfma_f32_16x16x32_bf16 v[14:17], v[180:183], v[220:223], v[14:17]
	v_mfma_f32_16x16x32_bf16 v[10:13], v[188:191], v[220:223], v[10:13]
	v_mfma_f32_16x16x32_bf16 v[6:9], v[180:183], v[228:231], v[6:9]
	v_mfma_f32_16x16x32_bf16 v[2:5], v[188:191], v[228:231], v[2:5]
	s_barrier
	s_setprio 0
	s_add_i32 s97, 0, 0x18000
	v_add_u32_e32 v154, s97, v169
	s_add_i32 vcc_lo, 0, 0x1c000
	ds_read_b128 v[146:149], v154
	ds_read_b128 v[150:153], v154 offset:1024
	ds_read_b128 v[164:167], v154 offset:2048
	ds_read_b128 v[172:175], v154 offset:3072
	v_add_u32_e32 v154, vcc_lo, v169
	ds_read_b128 v[176:179], v154
	ds_read_b128 v[180:183], v154 offset:1024
	ds_read_b128 v[184:187], v154 offset:2048
	ds_read_b128 v[188:191], v154 offset:3072
	s_add_u32 s40, s40, 0x80000
	s_addc_u32 s41, s41, 0
	s_mov_b32 m0, s83
	v_lshl_add_u64 v[238:239], s[40:41], 0, v[130:131]
	ds_read_b128 v[200:203], v171 offset:32768
	ds_read_b128 v[204:207], v171 offset:33792
	ds_read_b128 v[208:211], v171 offset:34816
	ds_read_b128 v[212:215], v171 offset:35840
	ds_read_b128 v[216:219], v171 offset:36864
	ds_read_b128 v[220:223], v171 offset:37888
	ds_read_b128 v[224:227], v171 offset:38912
	ds_read_b128 v[228:231], v171 offset:39936
	global_load_lds_dwordx4 v[238:239], off
	v_lshl_add_u64 v[238:239], s[40:41], 0, v[134:135]
	s_mov_b32 m0, s84
	s_nop 0
	global_load_lds_dwordx4 v[238:239], off
	s_waitcnt vmcnt(8)
	s_waitcnt lgkmcnt(0)
	s_barrier
	s_setprio 1
	s_waitcnt lgkmcnt(0)
	v_mfma_f32_16x16x32_bf16 v[126:129], v[146:149], v[200:203], v[126:129]
	v_mfma_f32_16x16x32_bf16 v[122:125], v[164:167], v[200:203], v[122:125]
	v_mfma_f32_16x16x32_bf16 v[118:121], v[146:149], v[208:211], v[118:121]
	v_mfma_f32_16x16x32_bf16 v[114:117], v[164:167], v[208:211], v[114:117]
	v_mfma_f32_16x16x32_bf16 v[110:113], v[146:149], v[216:219], v[110:113]
	v_mfma_f32_16x16x32_bf16 v[106:109], v[164:167], v[216:219], v[106:109]
	v_mfma_f32_16x16x32_bf16 v[102:105], v[146:149], v[224:227], v[102:105]
	v_mfma_f32_16x16x32_bf16 v[98:101], v[164:167], v[224:227], v[98:101]
	v_mfma_f32_16x16x32_bf16 v[126:129], v[150:153], v[204:207], v[126:129]
	v_mfma_f32_16x16x32_bf16 v[122:125], v[172:175], v[204:207], v[122:125]
	v_mfma_f32_16x16x32_bf16 v[118:121], v[150:153], v[212:215], v[118:121]
	v_mfma_f32_16x16x32_bf16 v[114:117], v[172:175], v[212:215], v[114:117]
	v_mfma_f32_16x16x32_bf16 v[110:113], v[150:153], v[220:223], v[110:113]
	v_mfma_f32_16x16x32_bf16 v[106:109], v[172:175], v[220:223], v[106:109]
	v_mfma_f32_16x16x32_bf16 v[102:105], v[150:153], v[228:231], v[102:105]
	v_mfma_f32_16x16x32_bf16 v[98:101], v[172:175], v[228:231], v[98:101]
	s_setprio 0
	s_setprio 1
	v_mfma_f32_16x16x32_bf16 v[94:97], v[176:179], v[200:203], v[94:97]
	v_mfma_f32_16x16x32_bf16 v[90:93], v[184:187], v[200:203], v[90:93]
	v_mfma_f32_16x16x32_bf16 v[86:89], v[176:179], v[208:211], v[86:89]
	v_mfma_f32_16x16x32_bf16 v[82:85], v[184:187], v[208:211], v[82:85]
	v_mfma_f32_16x16x32_bf16 v[78:81], v[176:179], v[216:219], v[78:81]
	v_mfma_f32_16x16x32_bf16 v[74:77], v[184:187], v[216:219], v[74:77]
	v_mfma_f32_16x16x32_bf16 v[70:73], v[176:179], v[224:227], v[70:73]
	v_mfma_f32_16x16x32_bf16 v[66:69], v[184:187], v[224:227], v[66:69]
	v_mfma_f32_16x16x32_bf16 v[94:97], v[180:183], v[204:207], v[94:97]
	v_mfma_f32_16x16x32_bf16 v[90:93], v[188:191], v[204:207], v[90:93]
	v_mfma_f32_16x16x32_bf16 v[86:89], v[180:183], v[212:215], v[86:89]
	v_mfma_f32_16x16x32_bf16 v[82:85], v[188:191], v[212:215], v[82:85]
	v_mfma_f32_16x16x32_bf16 v[78:81], v[180:183], v[220:223], v[78:81]
	v_mfma_f32_16x16x32_bf16 v[74:77], v[188:191], v[220:223], v[74:77]
	v_mfma_f32_16x16x32_bf16 v[70:73], v[180:183], v[228:231], v[70:73]
	v_mfma_f32_16x16x32_bf16 v[66:69], v[188:191], v[228:231], v[66:69]
	s_barrier
	s_setprio 0
	s_add_i32 s40, s97, s80
	v_lshl_add_u64 v[196:197], v[196:197], 0, s[34:35]
	s_mov_b32 m0, s40
	ds_read_b128 v[200:203], v171 offset:49152
	ds_read_b128 v[204:207], v171 offset:50176
	ds_read_b128 v[208:211], v171 offset:51200
	ds_read_b128 v[212:215], v171 offset:52224
	ds_read_b128 v[216:219], v171 offset:53248
	ds_read_b128 v[220:223], v171 offset:54272
	ds_read_b128 v[224:227], v171 offset:55296
	ds_read_b128 v[228:231], v171 offset:56320
	global_load_lds_dwordx4 v[196:197], off
	s_add_i32 m0, s40, 0x2000
	s_add_u32 s12, s12, 0x80080
	v_lshl_add_u64 v[196:197], v[232:233], 0, s[34:35]
	s_addc_u32 s13, s13, 0
	s_add_i32 s40, vcc_lo, s80
	global_load_lds_dwordx4 v[196:197], off
	v_lshl_add_u64 v[196:197], s[12:13], 0, v[132:133]
	s_mov_b32 m0, s40
	s_nop 0
	global_load_lds_dwordx4 v[196:197], off
	v_lshl_add_u64 v[196:197], s[12:13], 0, v[136:137]
	s_add_i32 m0, s40, 0x2000
	s_nop 0
	global_load_lds_dwordx4 v[196:197], off
	v_lshl_add_u64 v[196:197], v[234:235], 0, s[34:35]
	s_mov_b32 m0, s85
	s_nop 0
	global_load_lds_dwordx4 v[196:197], off
	v_lshl_add_u64 v[196:197], v[236:237], 0, s[34:35]
	s_mov_b32 m0, s86
	s_nop 0
	global_load_lds_dwordx4 v[196:197], off
	s_waitcnt vmcnt(8)
	s_waitcnt lgkmcnt(0)
	s_barrier
	s_setprio 1
	s_waitcnt lgkmcnt(0)
	v_mfma_f32_16x16x32_bf16 v[62:65], v[146:149], v[200:203], v[62:65]
	v_mfma_f32_16x16x32_bf16 v[58:61], v[164:167], v[200:203], v[58:61]
	v_mfma_f32_16x16x32_bf16 v[54:57], v[146:149], v[208:211], v[54:57]
	v_mfma_f32_16x16x32_bf16 v[50:53], v[164:167], v[208:211], v[50:53]
	v_mfma_f32_16x16x32_bf16 v[46:49], v[146:149], v[216:219], v[46:49]
	v_mfma_f32_16x16x32_bf16 v[42:45], v[164:167], v[216:219], v[42:45]
	v_mfma_f32_16x16x32_bf16 v[38:41], v[146:149], v[224:227], v[38:41]
	v_mfma_f32_16x16x32_bf16 v[34:37], v[164:167], v[224:227], v[34:37]
	v_mfma_f32_16x16x32_bf16 v[62:65], v[150:153], v[204:207], v[62:65]
	v_mfma_f32_16x16x32_bf16 v[58:61], v[172:175], v[204:207], v[58:61]
	v_mfma_f32_16x16x32_bf16 v[54:57], v[150:153], v[212:215], v[54:57]
	v_mfma_f32_16x16x32_bf16 v[50:53], v[172:175], v[212:215], v[50:53]
	v_mfma_f32_16x16x32_bf16 v[46:49], v[150:153], v[220:223], v[46:49]
	v_mfma_f32_16x16x32_bf16 v[42:45], v[172:175], v[220:223], v[42:45]
	v_mfma_f32_16x16x32_bf16 v[38:41], v[150:153], v[228:231], v[38:41]
	v_mfma_f32_16x16x32_bf16 v[34:37], v[172:175], v[228:231], v[34:37]
	s_setprio 0
	s_setprio 1
	v_mfma_f32_16x16x32_bf16 v[30:33], v[176:179], v[200:203], v[30:33]
	v_mfma_f32_16x16x32_bf16 v[26:29], v[184:187], v[200:203], v[26:29]
	v_mfma_f32_16x16x32_bf16 v[22:25], v[176:179], v[208:211], v[22:25]
	v_mfma_f32_16x16x32_bf16 v[18:21], v[184:187], v[208:211], v[18:21]
	v_mfma_f32_16x16x32_bf16 v[14:17], v[176:179], v[216:219], v[14:17]
	v_mfma_f32_16x16x32_bf16 v[10:13], v[184:187], v[216:219], v[10:13]
	v_mfma_f32_16x16x32_bf16 v[6:9], v[176:179], v[224:227], v[6:9]
	v_mfma_f32_16x16x32_bf16 v[2:5], v[184:187], v[224:227], v[2:5]
	v_mfma_f32_16x16x32_bf16 v[30:33], v[180:183], v[204:207], v[30:33]
	v_mfma_f32_16x16x32_bf16 v[26:29], v[188:191], v[204:207], v[26:29]
	v_mfma_f32_16x16x32_bf16 v[22:25], v[180:183], v[212:215], v[22:25]
	v_mfma_f32_16x16x32_bf16 v[18:21], v[188:191], v[212:215], v[18:21]
	v_mfma_f32_16x16x32_bf16 v[14:17], v[180:183], v[220:223], v[14:17]
	v_mfma_f32_16x16x32_bf16 v[10:13], v[188:191], v[220:223], v[10:13]
	v_mfma_f32_16x16x32_bf16 v[6:9], v[180:183], v[228:231], v[6:9]
	v_mfma_f32_16x16x32_bf16 v[2:5], v[188:191], v[228:231], v[2:5]
	s_barrier
	s_setprio 0
	s_add_i32 s96, s96, 2
	s_add_u32 s10, s10, 0x100
	s_addc_u32 s11, s11, 0
	s_cmp_gt_u32 s96, 29
	s_cbranch_scc0 .LBB0_290
	s_and_b64 vcc, exec, s[56:57]
	s_cbranch_vccz .LBB0_293
	s_barrier

.LBB0_473:
	s_add_u32 s64, s56, s10
	s_addc_u32 s65, s57, s11
	s_add_u32 s64, s64, 0x100
	s_addc_u32 s65, s65, 0
	s_add_u32 vcc_lo, s93, s10
	s_addc_u32 vcc_hi, s94, s11
	s_add_i32 s16, 0, 0x10000
	s_cmpk_eq_i32 s10, 0xf00
	s_cselect_b32 s67, s55, s65
	s_cselect_b32 s66, s95, s64
	s_cselect_b32 s65, s53, vcc_hi
	s_cselect_b32 s64, s96, vcc_lo
	s_add_i32 s24, 0, 0x14000
	v_add_u32_e32 v146, s16, v197
	v_add_u32_e32 v182, s24, v197
	ds_read_b128 v[134:137], v146
	ds_read_b128 v[138:141], v146 offset:1024
	ds_read_b128 v[142:145], v146 offset:2048
	ds_read_b128 v[146:149], v146 offset:3072
	ds_read_b128 v[150:153], v182
	ds_read_b128 v[174:177], v182 offset:1024
	ds_read_b128 v[178:181], v182 offset:2048
	ds_read_b128 v[182:185], v182 offset:3072
	v_lshl_add_u64 v[190:191], v[130:131], 0, s[10:11]
	s_add_i32 m0, s80, 0xc000
	ds_read_b128 v[186:189], v200
	ds_read_b128 v[202:205], v200 offset:1024
	ds_read_b128 v[206:209], v200 offset:2048
	ds_read_b128 v[210:213], v200 offset:3072
	ds_read_b128 v[214:217], v200 offset:4096
	ds_read_b128 v[218:221], v200 offset:5120
	ds_read_b128 v[222:225], v200 offset:6144
	ds_read_b128 v[226:229], v200 offset:7168
	global_load_lds_dwordx4 v[190:191], off
	v_lshl_add_u64 v[190:191], v[132:133], 0, s[10:11]
	s_add_i32 m0, s80, 0xe000
	s_nop 0
	global_load_lds_dwordx4 v[190:191], off
	s_waitcnt vmcnt(8)
	s_waitcnt lgkmcnt(0)
	s_barrier
	s_setprio 1
	s_waitcnt lgkmcnt(0)
	v_mfma_f32_16x16x32_bf16 v[126:129], v[134:137], v[186:189], v[126:129]
	v_mfma_f32_16x16x32_bf16 v[122:125], v[142:145], v[186:189], v[122:125]
	v_mfma_f32_16x16x32_bf16 v[118:121], v[134:137], v[206:209], v[118:121]
	v_mfma_f32_16x16x32_bf16 v[114:117], v[142:145], v[206:209], v[114:117]
	v_mfma_f32_16x16x32_bf16 v[110:113], v[134:137], v[214:217], v[110:113]
	v_mfma_f32_16x16x32_bf16 v[106:109], v[142:145], v[214:217], v[106:109]
	v_mfma_f32_16x16x32_bf16 v[102:105], v[134:137], v[222:225], v[102:105]
	v_mfma_f32_16x16x32_bf16 v[98:101], v[142:145], v[222:225], v[98:101]
	v_mfma_f32_16x16x32_bf16 v[126:129], v[138:141], v[202:205], v[126:129]
	v_mfma_f32_16x16x32_bf16 v[122:125], v[146:149], v[202:205], v[122:125]
	v_mfma_f32_16x16x32_bf16 v[118:121], v[138:141], v[210:213], v[118:121]
	v_mfma_f32_16x16x32_bf16 v[114:117], v[146:149], v[210:213], v[114:117]
	v_mfma_f32_16x16x32_bf16 v[110:113], v[138:141], v[218:221], v[110:113]
	v_mfma_f32_16x16x32_bf16 v[106:109], v[146:149], v[218:221], v[106:109]
	v_mfma_f32_16x16x32_bf16 v[102:105], v[138:141], v[226:229], v[102:105]
	v_mfma_f32_16x16x32_bf16 v[98:101], v[146:149], v[226:229], v[98:101]
	s_setprio 0
	s_setprio 1
	v_mfma_f32_16x16x32_bf16 v[94:97], v[150:153], v[186:189], v[94:97]
	v_mfma_f32_16x16x32_bf16 v[90:93], v[178:181], v[186:189], v[90:93]
	v_mfma_f32_16x16x32_bf16 v[86:89], v[150:153], v[206:209], v[86:89]
	v_mfma_f32_16x16x32_bf16 v[82:85], v[178:181], v[206:209], v[82:85]
	v_mfma_f32_16x16x32_bf16 v[78:81], v[150:153], v[214:217], v[78:81]
	v_mfma_f32_16x16x32_bf16 v[74:77], v[178:181], v[214:217], v[74:77]
	v_mfma_f32_16x16x32_bf16 v[70:73], v[150:153], v[222:225], v[70:73]
	v_mfma_f32_16x16x32_bf16 v[66:69], v[178:181], v[222:225], v[66:69]
	v_mfma_f32_16x16x32_bf16 v[94:97], v[174:177], v[202:205], v[94:97]
	v_mfma_f32_16x16x32_bf16 v[90:93], v[182:185], v[202:205], v[90:93]
	v_mfma_f32_16x16x32_bf16 v[86:89], v[174:177], v[210:213], v[86:89]
	v_mfma_f32_16x16x32_bf16 v[82:85], v[182:185], v[210:213], v[82:85]
	v_mfma_f32_16x16x32_bf16 v[78:81], v[174:177], v[218:221], v[78:81]
	v_mfma_f32_16x16x32_bf16 v[74:77], v[182:185], v[218:221], v[74:77]
	v_mfma_f32_16x16x32_bf16 v[70:73], v[174:177], v[226:229], v[70:73]
	v_mfma_f32_16x16x32_bf16 v[66:69], v[182:185], v[226:229], v[66:69]
	s_barrier
	s_setprio 0
	s_add_i32 s16, s16, s30
	v_lshl_add_u64 v[190:191], s[64:65], 0, v[154:155]
	s_mov_b32 m0, s16
	ds_read_b128 v[186:189], v200 offset:16384
	ds_read_b128 v[202:205], v200 offset:17408
	ds_read_b128 v[206:209], v200 offset:18432
	ds_read_b128 v[210:213], v200 offset:19456
	ds_read_b128 v[214:217], v200 offset:20480
	ds_read_b128 v[218:221], v200 offset:21504
	ds_read_b128 v[222:225], v200 offset:22528
	ds_read_b128 v[226:229], v200 offset:23552
	global_load_lds_dwordx4 v[190:191], off
	s_add_i32 m0, s16, 0x2000
	s_add_u32 vcc_lo, s64, 0x80000
	v_lshl_add_u64 v[230:231], s[64:65], 0, v[164:165]
	s_addc_u32 vcc_hi, s65, 0
	s_add_i32 s16, s24, s30
	global_load_lds_dwordx4 v[230:231], off
	v_lshl_add_u64 v[232:233], vcc, 0, v[154:155]
	s_mov_b32 m0, s16
	v_lshl_add_u64 v[234:235], s[66:67], 0, v[166:167]
	global_load_lds_dwordx4 v[232:233], off
	v_lshl_add_u64 v[232:233], vcc, 0, v[164:165]
	s_add_i32 m0, s16, 0x2000
	s_nop 0
	global_load_lds_dwordx4 v[232:233], off
	v_lshl_add_u64 v[232:233], s[66:67], 0, v[168:169]
	s_mov_b32 m0, s80
	s_nop 0
	global_load_lds_dwordx4 v[232:233], off
	s_mov_b32 m0, s81
	s_nop 0
	global_load_lds_dwordx4 v[234:235], off
	s_waitcnt vmcnt(8)
	s_waitcnt lgkmcnt(0)
	s_barrier
	s_setprio 1
	s_waitcnt lgkmcnt(0)
	v_mfma_f32_16x16x32_bf16 v[62:65], v[134:137], v[186:189], v[62:65]
	v_mfma_f32_16x16x32_bf16 v[58:61], v[142:145], v[186:189], v[58:61]
	v_mfma_f32_16x16x32_bf16 v[54:57], v[134:137], v[206:209], v[54:57]
	v_mfma_f32_16x16x32_bf16 v[50:53], v[142:145], v[206:209], v[50:53]
	v_mfma_f32_16x16x32_bf16 v[46:49], v[134:137], v[214:217], v[46:49]
	v_mfma_f32_16x16x32_bf16 v[42:45], v[142:145], v[214:217], v[42:45]
	v_mfma_f32_16x16x32_bf16 v[38:41], v[134:137], v[222:225], v[38:41]
	v_mfma_f32_16x16x32_bf16 v[34:37], v[142:145], v[222:225], v[34:37]
	v_mfma_f32_16x16x32_bf16 v[62:65], v[138:141], v[202:205], v[62:65]
	v_mfma_f32_16x16x32_bf16 v[58:61], v[146:149], v[202:205], v[58:61]
	v_mfma_f32_16x16x32_bf16 v[54:57], v[138:141], v[210:213], v[54:57]
	v_mfma_f32_16x16x32_bf16 v[50:53], v[146:149], v[210:213], v[50:53]
	v_mfma_f32_16x16x32_bf16 v[46:49], v[138:141], v[218:221], v[46:49]
	v_mfma_f32_16x16x32_bf16 v[42:45], v[146:149], v[218:221], v[42:45]
	v_mfma_f32_16x16x32_bf16 v[38:41], v[138:141], v[226:229], v[38:41]
	v_mfma_f32_16x16x32_bf16 v[34:37], v[146:149], v[226:229], v[34:37]
	s_setprio 0
	s_setprio 1
	v_mfma_f32_16x16x32_bf16 v[30:33], v[150:153], v[186:189], v[30:33]
	v_mfma_f32_16x16x32_bf16 v[26:29], v[178:181], v[186:189], v[26:29]
	v_mfma_f32_16x16x32_bf16 v[22:25], v[150:153], v[206:209], v[22:25]
	v_mfma_f32_16x16x32_bf16 v[18:21], v[178:181], v[206:209], v[18:21]
	v_mfma_f32_16x16x32_bf16 v[14:17], v[150:153], v[214:217], v[14:17]
	v_mfma_f32_16x16x32_bf16 v[10:13], v[178:181], v[214:217], v[10:13]
	v_mfma_f32_16x16x32_bf16 v[6:9], v[150:153], v[222:225], v[6:9]
	v_mfma_f32_16x16x32_bf16 v[2:5], v[178:181], v[222:225], v[2:5]
	v_mfma_f32_16x16x32_bf16 v[30:33], v[174:177], v[202:205], v[30:33]
	v_mfma_f32_16x16x32_bf16 v[26:29], v[182:185], v[202:205], v[26:29]
	v_mfma_f32_16x16x32_bf16 v[22:25], v[174:177], v[210:213], v[22:25]
	v_mfma_f32_16x16x32_bf16 v[18:21], v[182:185], v[210:213], v[18:21]
	v_mfma_f32_16x16x32_bf16 v[14:17], v[174:177], v[218:221], v[14:17]
	v_mfma_f32_16x16x32_bf16 v[10:13], v[182:185], v[218:221], v[10:13]
	v_mfma_f32_16x16x32_bf16 v[6:9], v[174:177], v[226:229], v[6:9]
	v_mfma_f32_16x16x32_bf16 v[2:5], v[182:185], v[226:229], v[2:5]
	s_barrier
	s_setprio 0
	s_add_i32 s16, 0, 0x18000
	s_add_i32 s24, 0, 0x1c000
	v_add_u32_e32 v146, s16, v197
	v_add_u32_e32 v182, s24, v197
	ds_read_b128 v[134:137], v146
	ds_read_b128 v[138:141], v146 offset:1024
	ds_read_b128 v[142:145], v146 offset:2048
	ds_read_b128 v[146:149], v146 offset:3072
	ds_read_b128 v[150:153], v182
	ds_read_b128 v[174:177], v182 offset:1024
	ds_read_b128 v[178:181], v182 offset:2048
	ds_read_b128 v[182:185], v182 offset:3072
	s_add_u32 s66, s66, 0x80000
	s_addc_u32 s67, s67, 0
	s_mov_b32 m0, s82
	v_lshl_add_u64 v[236:237], s[66:67], 0, v[168:169]
	ds_read_b128 v[186:189], v200 offset:32768
	ds_read_b128 v[202:205], v200 offset:33792
	ds_read_b128 v[206:209], v200 offset:34816
	ds_read_b128 v[210:213], v200 offset:35840
	ds_read_b128 v[214:217], v200 offset:36864
	ds_read_b128 v[218:221], v200 offset:37888
	ds_read_b128 v[222:225], v200 offset:38912
	ds_read_b128 v[226:229], v200 offset:39936
	global_load_lds_dwordx4 v[236:237], off
	v_lshl_add_u64 v[236:237], s[66:67], 0, v[166:167]
	s_mov_b32 m0, s83
	s_nop 0
	global_load_lds_dwordx4 v[236:237], off
	s_waitcnt vmcnt(8)
	s_waitcnt lgkmcnt(0)
	s_barrier
	s_setprio 1
	s_waitcnt lgkmcnt(0)
	v_mfma_f32_16x16x32_bf16 v[126:129], v[134:137], v[186:189], v[126:129]
	v_mfma_f32_16x16x32_bf16 v[122:125], v[142:145], v[186:189], v[122:125]
	v_mfma_f32_16x16x32_bf16 v[118:121], v[134:137], v[206:209], v[118:121]
	v_mfma_f32_16x16x32_bf16 v[114:117], v[142:145], v[206:209], v[114:117]
	v_mfma_f32_16x16x32_bf16 v[110:113], v[134:137], v[214:217], v[110:113]
	v_mfma_f32_16x16x32_bf16 v[106:109], v[142:145], v[214:217], v[106:109]
	v_mfma_f32_16x16x32_bf16 v[102:105], v[134:137], v[222:225], v[102:105]
	v_mfma_f32_16x16x32_bf16 v[98:101], v[142:145], v[222:225], v[98:101]
	v_mfma_f32_16x16x32_bf16 v[126:129], v[138:141], v[202:205], v[126:129]
	v_mfma_f32_16x16x32_bf16 v[122:125], v[146:149], v[202:205], v[122:125]
	v_mfma_f32_16x16x32_bf16 v[118:121], v[138:141], v[210:213], v[118:121]
	v_mfma_f32_16x16x32_bf16 v[114:117], v[146:149], v[210:213], v[114:117]
	v_mfma_f32_16x16x32_bf16 v[110:113], v[138:141], v[218:221], v[110:113]
	v_mfma_f32_16x16x32_bf16 v[106:109], v[146:149], v[218:221], v[106:109]
	v_mfma_f32_16x16x32_bf16 v[102:105], v[138:141], v[226:229], v[102:105]
	v_mfma_f32_16x16x32_bf16 v[98:101], v[146:149], v[226:229], v[98:101]
	s_setprio 0
	s_setprio 1
	v_mfma_f32_16x16x32_bf16 v[94:97], v[150:153], v[186:189], v[94:97]
	v_mfma_f32_16x16x32_bf16 v[90:93], v[178:181], v[186:189], v[90:93]
	v_mfma_f32_16x16x32_bf16 v[86:89], v[150:153], v[206:209], v[86:89]
	v_mfma_f32_16x16x32_bf16 v[82:85], v[178:181], v[206:209], v[82:85]
	v_mfma_f32_16x16x32_bf16 v[78:81], v[150:153], v[214:217], v[78:81]
	v_mfma_f32_16x16x32_bf16 v[74:77], v[178:181], v[214:217], v[74:77]
	v_mfma_f32_16x16x32_bf16 v[70:73], v[150:153], v[222:225], v[70:73]
	v_mfma_f32_16x16x32_bf16 v[66:69], v[178:181], v[222:225], v[66:69]
	v_mfma_f32_16x16x32_bf16 v[94:97], v[174:177], v[202:205], v[94:97]
	v_mfma_f32_16x16x32_bf16 v[90:93], v[182:185], v[202:205], v[90:93]
	v_mfma_f32_16x16x32_bf16 v[86:89], v[174:177], v[210:213], v[86:89]
	v_mfma_f32_16x16x32_bf16 v[82:85], v[182:185], v[210:213], v[82:85]
	v_mfma_f32_16x16x32_bf16 v[78:81], v[174:177], v[218:221], v[78:81]
	v_mfma_f32_16x16x32_bf16 v[74:77], v[182:185], v[218:221], v[74:77]
	v_mfma_f32_16x16x32_bf16 v[70:73], v[174:177], v[226:229], v[70:73]
	v_mfma_f32_16x16x32_bf16 v[66:69], v[182:185], v[226:229], v[66:69]
	s_barrier
	s_setprio 0
	s_add_i32 s16, s16, s30
	v_lshl_add_u64 v[190:191], v[190:191], 0, s[34:35]
	s_mov_b32 m0, s16
	ds_read_b128 v[186:189], v200 offset:49152
	ds_read_b128 v[202:205], v200 offset:50176
	ds_read_b128 v[206:209], v200 offset:51200
	ds_read_b128 v[210:213], v200 offset:52224
	ds_read_b128 v[214:217], v200 offset:53248
	ds_read_b128 v[218:221], v200 offset:54272
	ds_read_b128 v[222:225], v200 offset:55296
	ds_read_b128 v[226:229], v200 offset:56320
	global_load_lds_dwordx4 v[190:191], off
	s_add_i32 m0, s16, 0x2000
	s_add_u32 s64, s64, 0x80080
	v_lshl_add_u64 v[190:191], v[230:231], 0, s[34:35]
	s_addc_u32 s65, s65, 0
	s_add_i32 s16, s24, s30
	global_load_lds_dwordx4 v[190:191], off
	v_lshl_add_u64 v[190:191], s[64:65], 0, v[154:155]
	s_mov_b32 m0, s16
	s_nop 0
	global_load_lds_dwordx4 v[190:191], off
	v_lshl_add_u64 v[190:191], s[64:65], 0, v[164:165]
	s_add_i32 m0, s16, 0x2000
	s_nop 0
	global_load_lds_dwordx4 v[190:191], off
	v_lshl_add_u64 v[190:191], v[232:233], 0, s[34:35]
	s_mov_b32 m0, s84
	s_nop 0
	global_load_lds_dwordx4 v[190:191], off
	v_lshl_add_u64 v[190:191], v[234:235], 0, s[34:35]
	s_mov_b32 m0, s85
	s_nop 0
	global_load_lds_dwordx4 v[190:191], off
	s_waitcnt vmcnt(8)
	s_waitcnt lgkmcnt(0)
	s_barrier
	s_setprio 1
	s_waitcnt lgkmcnt(0)
	v_mfma_f32_16x16x32_bf16 v[62:65], v[134:137], v[186:189], v[62:65]
	v_mfma_f32_16x16x32_bf16 v[58:61], v[142:145], v[186:189], v[58:61]
	v_mfma_f32_16x16x32_bf16 v[54:57], v[134:137], v[206:209], v[54:57]
	v_mfma_f32_16x16x32_bf16 v[50:53], v[142:145], v[206:209], v[50:53]
	v_mfma_f32_16x16x32_bf16 v[46:49], v[134:137], v[214:217], v[46:49]
	v_mfma_f32_16x16x32_bf16 v[42:45], v[142:145], v[214:217], v[42:45]
	v_mfma_f32_16x16x32_bf16 v[38:41], v[134:137], v[222:225], v[38:41]
	v_mfma_f32_16x16x32_bf16 v[34:37], v[142:145], v[222:225], v[34:37]
	v_mfma_f32_16x16x32_bf16 v[62:65], v[138:141], v[202:205], v[62:65]
	v_mfma_f32_16x16x32_bf16 v[58:61], v[146:149], v[202:205], v[58:61]
	v_mfma_f32_16x16x32_bf16 v[54:57], v[138:141], v[210:213], v[54:57]
	v_mfma_f32_16x16x32_bf16 v[50:53], v[146:149], v[210:213], v[50:53]
	v_mfma_f32_16x16x32_bf16 v[46:49], v[138:141], v[218:221], v[46:49]
	v_mfma_f32_16x16x32_bf16 v[42:45], v[146:149], v[218:221], v[42:45]
	v_mfma_f32_16x16x32_bf16 v[38:41], v[138:141], v[226:229], v[38:41]
	v_mfma_f32_16x16x32_bf16 v[34:37], v[146:149], v[226:229], v[34:37]
	s_setprio 0
	s_setprio 1
	v_mfma_f32_16x16x32_bf16 v[30:33], v[150:153], v[186:189], v[30:33]
	v_mfma_f32_16x16x32_bf16 v[26:29], v[178:181], v[186:189], v[26:29]
	v_mfma_f32_16x16x32_bf16 v[22:25], v[150:153], v[206:209], v[22:25]
	v_mfma_f32_16x16x32_bf16 v[18:21], v[178:181], v[206:209], v[18:21]
	v_mfma_f32_16x16x32_bf16 v[14:17], v[150:153], v[214:217], v[14:17]
	v_mfma_f32_16x16x32_bf16 v[10:13], v[178:181], v[214:217], v[10:13]
	v_mfma_f32_16x16x32_bf16 v[6:9], v[150:153], v[222:225], v[6:9]
	v_mfma_f32_16x16x32_bf16 v[2:5], v[178:181], v[222:225], v[2:5]
	v_mfma_f32_16x16x32_bf16 v[30:33], v[174:177], v[202:205], v[30:33]
	v_mfma_f32_16x16x32_bf16 v[26:29], v[182:185], v[202:205], v[26:29]
	v_mfma_f32_16x16x32_bf16 v[22:25], v[174:177], v[210:213], v[22:25]
	v_mfma_f32_16x16x32_bf16 v[18:21], v[182:185], v[210:213], v[18:21]
	v_mfma_f32_16x16x32_bf16 v[14:17], v[174:177], v[218:221], v[14:17]
	v_mfma_f32_16x16x32_bf16 v[10:13], v[182:185], v[218:221], v[10:13]
	v_mfma_f32_16x16x32_bf16 v[6:9], v[174:177], v[226:229], v[6:9]
	v_mfma_f32_16x16x32_bf16 v[2:5], v[182:185], v[226:229], v[2:5]
	s_barrier
	s_setprio 0
	s_add_i32 s97, s97, 2
	s_add_u32 s10, s10, 0x100
	s_addc_u32 s11, s11, 0
	s_cmp_gt_u32 s97, 29
	s_cbranch_scc0 .LBB0_473
	s_and_b64 vcc, exec, s[46:47]
	s_cbranch_vccz .LBB0_476
	s_barrier

.LBB0_623:
	s_add_u32 s8, s52, s0
	s_addc_u32 s9, s53, s1
	s_add_u32 s8, s8, 0x100
	s_addc_u32 s9, s9, 0
	s_add_u32 s55, s76, s0
	s_addc_u32 s78, s77, s1
	s_add_i32 s79, 0, 0x10000
	s_cmpk_eq_i32 s0, 0xf00
	s_cselect_b32 s11, s12, s9
	s_cselect_b32 s10, s13, s8
	s_cselect_b32 s9, s26, s78
	s_cselect_b32 s8, s27, s55
	s_add_i32 s55, 0, 0x14000
	v_add_u32_e32 v148, s79, v204
	v_add_u32_e32 v186, s55, v204
	ds_read_b128 v[136:139], v148
	ds_read_b128 v[140:143], v148 offset:1024
	ds_read_b128 v[144:147], v148 offset:2048
	ds_read_b128 v[148:151], v148 offset:3072
	ds_read_b128 v[152:155], v186
	ds_read_b128 v[156:159], v186 offset:1024
	ds_read_b128 v[160:163], v186 offset:2048
	ds_read_b128 v[186:189], v186 offset:3072
	v_lshl_add_u64 v[230:231], v[132:133], 0, s[0:1]
	s_add_i32 m0, s25, 0xc000
	ds_read_b128 v[190:193], v205
	ds_read_b128 v[194:197], v205 offset:1024
	ds_read_b128 v[206:209], v205 offset:2048
	ds_read_b128 v[210:213], v205 offset:3072
	ds_read_b128 v[214:217], v205 offset:4096
	ds_read_b128 v[218:221], v205 offset:5120
	ds_read_b128 v[222:225], v205 offset:6144
	ds_read_b128 v[226:229], v205 offset:7168
	global_load_lds_dwordx4 v[230:231], off
	v_lshl_add_u64 v[230:231], v[134:135], 0, s[0:1]
	s_add_i32 m0, s25, 0xe000
	s_nop 0
	global_load_lds_dwordx4 v[230:231], off
	s_waitcnt vmcnt(8)
	s_waitcnt lgkmcnt(0)
	s_barrier
	s_setprio 1
	s_waitcnt lgkmcnt(0)
	v_mfma_f32_16x16x32_bf16 v[128:131], v[136:139], v[190:193], v[128:131]
	v_mfma_f32_16x16x32_bf16 v[124:127], v[144:147], v[190:193], v[124:127]
	v_mfma_f32_16x16x32_bf16 v[120:123], v[136:139], v[206:209], v[120:123]
	v_mfma_f32_16x16x32_bf16 v[116:119], v[144:147], v[206:209], v[116:119]
	v_mfma_f32_16x16x32_bf16 v[112:115], v[136:139], v[214:217], v[112:115]
	v_mfma_f32_16x16x32_bf16 v[108:111], v[144:147], v[214:217], v[108:111]
	v_mfma_f32_16x16x32_bf16 v[104:107], v[136:139], v[222:225], v[104:107]
	v_mfma_f32_16x16x32_bf16 v[100:103], v[144:147], v[222:225], v[100:103]
	v_mfma_f32_16x16x32_bf16 v[128:131], v[140:143], v[194:197], v[128:131]
	v_mfma_f32_16x16x32_bf16 v[124:127], v[148:151], v[194:197], v[124:127]
	v_mfma_f32_16x16x32_bf16 v[120:123], v[140:143], v[210:213], v[120:123]
	v_mfma_f32_16x16x32_bf16 v[116:119], v[148:151], v[210:213], v[116:119]
	v_mfma_f32_16x16x32_bf16 v[112:115], v[140:143], v[218:221], v[112:115]
	v_mfma_f32_16x16x32_bf16 v[108:111], v[148:151], v[218:221], v[108:111]
	v_mfma_f32_16x16x32_bf16 v[104:107], v[140:143], v[226:229], v[104:107]
	v_mfma_f32_16x16x32_bf16 v[100:103], v[148:151], v[226:229], v[100:103]
	s_setprio 0
	s_setprio 1
	v_mfma_f32_16x16x32_bf16 v[96:99], v[152:155], v[190:193], v[96:99]
	v_mfma_f32_16x16x32_bf16 v[92:95], v[160:163], v[190:193], v[92:95]
	v_mfma_f32_16x16x32_bf16 v[88:91], v[152:155], v[206:209], v[88:91]
	v_mfma_f32_16x16x32_bf16 v[84:87], v[160:163], v[206:209], v[84:87]
	v_mfma_f32_16x16x32_bf16 v[80:83], v[152:155], v[214:217], v[80:83]
	v_mfma_f32_16x16x32_bf16 v[76:79], v[160:163], v[214:217], v[76:79]
	v_mfma_f32_16x16x32_bf16 v[72:75], v[152:155], v[222:225], v[72:75]
	v_mfma_f32_16x16x32_bf16 v[68:71], v[160:163], v[222:225], v[68:71]
	v_mfma_f32_16x16x32_bf16 v[96:99], v[156:159], v[194:197], v[96:99]
	v_mfma_f32_16x16x32_bf16 v[92:95], v[186:189], v[194:197], v[92:95]
	v_mfma_f32_16x16x32_bf16 v[88:91], v[156:159], v[210:213], v[88:91]
	v_mfma_f32_16x16x32_bf16 v[84:87], v[186:189], v[210:213], v[84:87]
	v_mfma_f32_16x16x32_bf16 v[80:83], v[156:159], v[218:221], v[80:83]
	v_mfma_f32_16x16x32_bf16 v[76:79], v[186:189], v[218:221], v[76:79]
	v_mfma_f32_16x16x32_bf16 v[72:75], v[156:159], v[226:229], v[72:75]
	v_mfma_f32_16x16x32_bf16 v[68:71], v[186:189], v[226:229], v[68:71]
	s_barrier
	s_setprio 0
	s_add_i32 s78, s79, s24
	v_lshl_add_u64 v[230:231], s[8:9], 0, v[170:171]
	s_mov_b32 m0, s78
	ds_read_b128 v[190:193], v205 offset:16384
	ds_read_b128 v[194:197], v205 offset:17408
	ds_read_b128 v[206:209], v205 offset:18432
	ds_read_b128 v[210:213], v205 offset:19456
	ds_read_b128 v[214:217], v205 offset:20480
	ds_read_b128 v[218:221], v205 offset:21504
	ds_read_b128 v[222:225], v205 offset:22528
	ds_read_b128 v[226:229], v205 offset:23552
	global_load_lds_dwordx4 v[230:231], off
	s_add_i32 m0, s78, 0x2000
	s_add_u32 s78, s8, 0x80000
	v_lshl_add_u64 v[232:233], s[8:9], 0, v[174:175]
	s_addc_u32 s79, s9, 0
	s_add_i32 s55, s55, s24
	global_load_lds_dwordx4 v[232:233], off
	v_lshl_add_u64 v[234:235], s[78:79], 0, v[170:171]
	s_mov_b32 m0, s55
	v_lshl_add_u64 v[236:237], s[10:11], 0, v[172:173]
	global_load_lds_dwordx4 v[234:235], off
	v_lshl_add_u64 v[234:235], s[78:79], 0, v[174:175]
	s_add_i32 m0, s55, 0x2000
	s_nop 0
	global_load_lds_dwordx4 v[234:235], off
	v_lshl_add_u64 v[234:235], s[10:11], 0, v[168:169]
	s_mov_b32 m0, s25
	s_nop 0
	global_load_lds_dwordx4 v[234:235], off
	s_mov_b32 m0, s30
	s_nop 0
	global_load_lds_dwordx4 v[236:237], off
	s_waitcnt vmcnt(8)
	s_waitcnt lgkmcnt(0)
	s_barrier
	s_setprio 1
	s_waitcnt lgkmcnt(0)
	v_mfma_f32_16x16x32_bf16 v[64:67], v[136:139], v[190:193], v[64:67]
	v_mfma_f32_16x16x32_bf16 v[60:63], v[144:147], v[190:193], v[60:63]
	v_mfma_f32_16x16x32_bf16 v[56:59], v[136:139], v[206:209], v[56:59]
	v_mfma_f32_16x16x32_bf16 v[52:55], v[144:147], v[206:209], v[52:55]
	v_mfma_f32_16x16x32_bf16 v[48:51], v[136:139], v[214:217], v[48:51]
	v_mfma_f32_16x16x32_bf16 v[44:47], v[144:147], v[214:217], v[44:47]
	v_mfma_f32_16x16x32_bf16 v[40:43], v[136:139], v[222:225], v[40:43]
	v_mfma_f32_16x16x32_bf16 v[36:39], v[144:147], v[222:225], v[36:39]
	v_mfma_f32_16x16x32_bf16 v[64:67], v[140:143], v[194:197], v[64:67]
	v_mfma_f32_16x16x32_bf16 v[60:63], v[148:151], v[194:197], v[60:63]
	v_mfma_f32_16x16x32_bf16 v[56:59], v[140:143], v[210:213], v[56:59]
	v_mfma_f32_16x16x32_bf16 v[52:55], v[148:151], v[210:213], v[52:55]
	v_mfma_f32_16x16x32_bf16 v[48:51], v[140:143], v[218:221], v[48:51]
	v_mfma_f32_16x16x32_bf16 v[44:47], v[148:151], v[218:221], v[44:47]
	v_mfma_f32_16x16x32_bf16 v[40:43], v[140:143], v[226:229], v[40:43]
	v_mfma_f32_16x16x32_bf16 v[36:39], v[148:151], v[226:229], v[36:39]
	s_setprio 0
	s_setprio 1
	v_mfma_f32_16x16x32_bf16 v[32:35], v[152:155], v[190:193], v[32:35]
	v_mfma_f32_16x16x32_bf16 v[28:31], v[160:163], v[190:193], v[28:31]
	v_mfma_f32_16x16x32_bf16 v[24:27], v[152:155], v[206:209], v[24:27]
	v_mfma_f32_16x16x32_bf16 v[20:23], v[160:163], v[206:209], v[20:23]
	v_mfma_f32_16x16x32_bf16 v[16:19], v[152:155], v[214:217], v[16:19]
	v_mfma_f32_16x16x32_bf16 v[12:15], v[160:163], v[214:217], v[12:15]
	v_mfma_f32_16x16x32_bf16 v[8:11], v[152:155], v[222:225], v[8:11]
	v_mfma_f32_16x16x32_bf16 v[4:7], v[160:163], v[222:225], v[4:7]
	v_mfma_f32_16x16x32_bf16 v[32:35], v[156:159], v[194:197], v[32:35]
	v_mfma_f32_16x16x32_bf16 v[28:31], v[186:189], v[194:197], v[28:31]
	v_mfma_f32_16x16x32_bf16 v[24:27], v[156:159], v[210:213], v[24:27]
	v_mfma_f32_16x16x32_bf16 v[20:23], v[186:189], v[210:213], v[20:23]
	v_mfma_f32_16x16x32_bf16 v[16:19], v[156:159], v[218:221], v[16:19]
	v_mfma_f32_16x16x32_bf16 v[12:15], v[186:189], v[218:221], v[12:15]
	v_mfma_f32_16x16x32_bf16 v[8:11], v[156:159], v[226:229], v[8:11]
	v_mfma_f32_16x16x32_bf16 v[4:7], v[186:189], v[226:229], v[4:7]
	s_barrier
	s_setprio 0
	s_add_i32 s55, 0, 0x18000
	s_add_i32 s78, 0, 0x1c000
	v_add_u32_e32 v148, s55, v204
	v_add_u32_e32 v186, s78, v204
	ds_read_b128 v[136:139], v148
	ds_read_b128 v[140:143], v148 offset:1024
	ds_read_b128 v[144:147], v148 offset:2048
	ds_read_b128 v[148:151], v148 offset:3072
	ds_read_b128 v[152:155], v186
	ds_read_b128 v[156:159], v186 offset:1024
	ds_read_b128 v[160:163], v186 offset:2048
	ds_read_b128 v[186:189], v186 offset:3072
	s_add_u32 s10, s10, 0x80000
	s_addc_u32 s11, s11, 0
	s_mov_b32 m0, s31
	v_lshl_add_u64 v[238:239], s[10:11], 0, v[168:169]
	ds_read_b128 v[190:193], v205 offset:32768
	ds_read_b128 v[194:197], v205 offset:33792
	ds_read_b128 v[206:209], v205 offset:34816
	ds_read_b128 v[210:213], v205 offset:35840
	ds_read_b128 v[214:217], v205 offset:36864
	ds_read_b128 v[218:221], v205 offset:37888
	ds_read_b128 v[222:225], v205 offset:38912
	ds_read_b128 v[226:229], v205 offset:39936
	global_load_lds_dwordx4 v[238:239], off
	v_lshl_add_u64 v[238:239], s[10:11], 0, v[172:173]
	s_mov_b32 m0, s36
	s_nop 0
	global_load_lds_dwordx4 v[238:239], off
	s_waitcnt vmcnt(8)
	s_waitcnt lgkmcnt(0)
	s_barrier
	s_setprio 1
	s_waitcnt lgkmcnt(0)
	v_mfma_f32_16x16x32_bf16 v[128:131], v[136:139], v[190:193], v[128:131]
	v_mfma_f32_16x16x32_bf16 v[124:127], v[144:147], v[190:193], v[124:127]
	v_mfma_f32_16x16x32_bf16 v[120:123], v[136:139], v[206:209], v[120:123]
	v_mfma_f32_16x16x32_bf16 v[116:119], v[144:147], v[206:209], v[116:119]
	v_mfma_f32_16x16x32_bf16 v[112:115], v[136:139], v[214:217], v[112:115]
	v_mfma_f32_16x16x32_bf16 v[108:111], v[144:147], v[214:217], v[108:111]
	v_mfma_f32_16x16x32_bf16 v[104:107], v[136:139], v[222:225], v[104:107]
	v_mfma_f32_16x16x32_bf16 v[100:103], v[144:147], v[222:225], v[100:103]
	v_mfma_f32_16x16x32_bf16 v[128:131], v[140:143], v[194:197], v[128:131]
	v_mfma_f32_16x16x32_bf16 v[124:127], v[148:151], v[194:197], v[124:127]
	v_mfma_f32_16x16x32_bf16 v[120:123], v[140:143], v[210:213], v[120:123]
	v_mfma_f32_16x16x32_bf16 v[116:119], v[148:151], v[210:213], v[116:119]
	v_mfma_f32_16x16x32_bf16 v[112:115], v[140:143], v[218:221], v[112:115]
	v_mfma_f32_16x16x32_bf16 v[108:111], v[148:151], v[218:221], v[108:111]
	v_mfma_f32_16x16x32_bf16 v[104:107], v[140:143], v[226:229], v[104:107]
	v_mfma_f32_16x16x32_bf16 v[100:103], v[148:151], v[226:229], v[100:103]
	s_setprio 0
	s_setprio 1
	v_mfma_f32_16x16x32_bf16 v[96:99], v[152:155], v[190:193], v[96:99]
	v_mfma_f32_16x16x32_bf16 v[92:95], v[160:163], v[190:193], v[92:95]
	v_mfma_f32_16x16x32_bf16 v[88:91], v[152:155], v[206:209], v[88:91]
	v_mfma_f32_16x16x32_bf16 v[84:87], v[160:163], v[206:209], v[84:87]
	v_mfma_f32_16x16x32_bf16 v[80:83], v[152:155], v[214:217], v[80:83]
	v_mfma_f32_16x16x32_bf16 v[76:79], v[160:163], v[214:217], v[76:79]
	v_mfma_f32_16x16x32_bf16 v[72:75], v[152:155], v[222:225], v[72:75]
	v_mfma_f32_16x16x32_bf16 v[68:71], v[160:163], v[222:225], v[68:71]
	v_mfma_f32_16x16x32_bf16 v[96:99], v[156:159], v[194:197], v[96:99]
	v_mfma_f32_16x16x32_bf16 v[92:95], v[186:189], v[194:197], v[92:95]
	v_mfma_f32_16x16x32_bf16 v[88:91], v[156:159], v[210:213], v[88:91]
	v_mfma_f32_16x16x32_bf16 v[84:87], v[186:189], v[210:213], v[84:87]
	v_mfma_f32_16x16x32_bf16 v[80:83], v[156:159], v[218:221], v[80:83]
	v_mfma_f32_16x16x32_bf16 v[76:79], v[186:189], v[218:221], v[76:79]
	v_mfma_f32_16x16x32_bf16 v[72:75], v[156:159], v[226:229], v[72:75]
	v_mfma_f32_16x16x32_bf16 v[68:71], v[186:189], v[226:229], v[68:71]
	s_barrier
	s_setprio 0
	s_add_i32 s10, s55, s24
	v_lshl_add_u64 v[230:231], v[230:231], 0, s[28:29]
	s_mov_b32 m0, s10
	ds_read_b128 v[190:193], v205 offset:49152
	ds_read_b128 v[194:197], v205 offset:50176
	ds_read_b128 v[206:209], v205 offset:51200
	ds_read_b128 v[210:213], v205 offset:52224
	ds_read_b128 v[214:217], v205 offset:53248
	ds_read_b128 v[218:221], v205 offset:54272
	ds_read_b128 v[222:225], v205 offset:55296
	ds_read_b128 v[226:229], v205 offset:56320
	global_load_lds_dwordx4 v[230:231], off
	s_add_i32 m0, s10, 0x2000
	s_add_u32 s8, s8, 0x80080
	v_lshl_add_u64 v[230:231], v[232:233], 0, s[28:29]
	s_addc_u32 s9, s9, 0
	s_add_i32 s10, s78, s24
	global_load_lds_dwordx4 v[230:231], off
	v_lshl_add_u64 v[230:231], s[8:9], 0, v[170:171]
	s_mov_b32 m0, s10
	s_nop 0
	global_load_lds_dwordx4 v[230:231], off
	v_lshl_add_u64 v[230:231], s[8:9], 0, v[174:175]
	s_add_i32 m0, s10, 0x2000
	s_nop 0
	global_load_lds_dwordx4 v[230:231], off
	v_lshl_add_u64 v[230:231], v[234:235], 0, s[28:29]
	s_mov_b32 m0, s45
	s_nop 0
	global_load_lds_dwordx4 v[230:231], off
	v_lshl_add_u64 v[230:231], v[236:237], 0, s[28:29]
	s_mov_b32 m0, s60
	s_nop 0
	global_load_lds_dwordx4 v[230:231], off
	s_waitcnt vmcnt(8)
	s_waitcnt lgkmcnt(0)
	s_barrier
	s_setprio 1
	s_waitcnt lgkmcnt(0)
	v_mfma_f32_16x16x32_bf16 v[64:67], v[136:139], v[190:193], v[64:67]
	v_mfma_f32_16x16x32_bf16 v[60:63], v[144:147], v[190:193], v[60:63]
	v_mfma_f32_16x16x32_bf16 v[56:59], v[136:139], v[206:209], v[56:59]
	v_mfma_f32_16x16x32_bf16 v[52:55], v[144:147], v[206:209], v[52:55]
	v_mfma_f32_16x16x32_bf16 v[48:51], v[136:139], v[214:217], v[48:51]
	v_mfma_f32_16x16x32_bf16 v[44:47], v[144:147], v[214:217], v[44:47]
	v_mfma_f32_16x16x32_bf16 v[40:43], v[136:139], v[222:225], v[40:43]
	v_mfma_f32_16x16x32_bf16 v[36:39], v[144:147], v[222:225], v[36:39]
	v_mfma_f32_16x16x32_bf16 v[64:67], v[140:143], v[194:197], v[64:67]
	v_mfma_f32_16x16x32_bf16 v[60:63], v[148:151], v[194:197], v[60:63]
	v_mfma_f32_16x16x32_bf16 v[56:59], v[140:143], v[210:213], v[56:59]
	v_mfma_f32_16x16x32_bf16 v[52:55], v[148:151], v[210:213], v[52:55]
	v_mfma_f32_16x16x32_bf16 v[48:51], v[140:143], v[218:221], v[48:51]
	v_mfma_f32_16x16x32_bf16 v[44:47], v[148:151], v[218:221], v[44:47]
	v_mfma_f32_16x16x32_bf16 v[40:43], v[140:143], v[226:229], v[40:43]
	v_mfma_f32_16x16x32_bf16 v[36:39], v[148:151], v[226:229], v[36:39]
	s_setprio 0
	s_setprio 1
	v_mfma_f32_16x16x32_bf16 v[32:35], v[152:155], v[190:193], v[32:35]
	v_mfma_f32_16x16x32_bf16 v[28:31], v[160:163], v[190:193], v[28:31]
	v_mfma_f32_16x16x32_bf16 v[24:27], v[152:155], v[206:209], v[24:27]
	v_mfma_f32_16x16x32_bf16 v[20:23], v[160:163], v[206:209], v[20:23]
	v_mfma_f32_16x16x32_bf16 v[16:19], v[152:155], v[214:217], v[16:19]
	v_mfma_f32_16x16x32_bf16 v[12:15], v[160:163], v[214:217], v[12:15]
	v_mfma_f32_16x16x32_bf16 v[8:11], v[152:155], v[222:225], v[8:11]
	v_mfma_f32_16x16x32_bf16 v[4:7], v[160:163], v[222:225], v[4:7]
	v_mfma_f32_16x16x32_bf16 v[32:35], v[156:159], v[194:197], v[32:35]
	v_mfma_f32_16x16x32_bf16 v[28:31], v[186:189], v[194:197], v[28:31]
	v_mfma_f32_16x16x32_bf16 v[24:27], v[156:159], v[210:213], v[24:27]
	v_mfma_f32_16x16x32_bf16 v[20:23], v[186:189], v[210:213], v[20:23]
	v_mfma_f32_16x16x32_bf16 v[16:19], v[156:159], v[218:221], v[16:19]
	v_mfma_f32_16x16x32_bf16 v[12:15], v[186:189], v[218:221], v[12:15]
	v_mfma_f32_16x16x32_bf16 v[8:11], v[156:159], v[226:229], v[8:11]
	v_mfma_f32_16x16x32_bf16 v[4:7], v[186:189], v[226:229], v[4:7]
	s_barrier
	s_setprio 0
	s_add_i32 s43, s43, 2
	s_add_u32 s0, s0, 0x100
	s_addc_u32 s1, s1, 0
	s_cmp_gt_u32 s43, 29
	s_cbranch_scc0 .LBB0_623
	s_and_b64 vcc, exec, s[50:51]
	s_cbranch_vccz .LBB0_626
	s_barrier

.LBB0_866:
	s_add_u32 s24, s34, s10
	s_addc_u32 s25, s35, s11
	s_add_u32 s24, s24, 0x100
	s_addc_u32 s25, s25, 0
	s_add_u32 s67, s60, s10
	s_addc_u32 s74, s61, s11
	s_add_i32 s75, 0, 0x10000
	s_cmpk_eq_i32 s10, 0xf00
	s_cselect_b32 s31, s27, s25
	s_cselect_b32 s30, s62, s24
	s_cselect_b32 s25, s15, s74
	s_cselect_b32 s24, s63, s67
	s_add_i32 s67, 0, 0x14000
	v_add_u32_e32 v148, s75, v189
	v_add_u32_e32 v178, s67, v189
	ds_read_b128 v[136:139], v148
	ds_read_b128 v[140:143], v148 offset:1024
	ds_read_b128 v[144:147], v148 offset:2048
	ds_read_b128 v[148:151], v148 offset:3072
	ds_read_b128 v[152:155], v178
	ds_read_b128 v[170:173], v178 offset:1024
	ds_read_b128 v[174:177], v178 offset:2048
	ds_read_b128 v[178:181], v178 offset:3072
	v_lshl_add_u64 v[186:187], v[132:133], 0, s[10:11]
	s_add_i32 m0, s48, 0xc000
	ds_read_b128 v[182:185], v191
	ds_read_b128 v[192:195], v191 offset:1024
	ds_read_b128 v[204:207], v191 offset:2048
	ds_read_b128 v[208:211], v191 offset:3072
	ds_read_b128 v[212:215], v191 offset:4096
	ds_read_b128 v[216:219], v191 offset:5120
	ds_read_b128 v[220:223], v191 offset:6144
	ds_read_b128 v[224:227], v191 offset:7168
	global_load_lds_dwordx4 v[186:187], off
	v_lshl_add_u64 v[186:187], v[134:135], 0, s[10:11]
	s_add_i32 m0, s48, 0xe000
	s_nop 0
	global_load_lds_dwordx4 v[186:187], off
	s_waitcnt vmcnt(8)
	s_waitcnt lgkmcnt(0)
	s_barrier
	s_setprio 1
	s_waitcnt lgkmcnt(0)
	v_mfma_f32_16x16x32_bf16 v[128:131], v[136:139], v[182:185], v[128:131]
	v_mfma_f32_16x16x32_bf16 v[124:127], v[144:147], v[182:185], v[124:127]
	v_mfma_f32_16x16x32_bf16 v[120:123], v[136:139], v[204:207], v[120:123]
	v_mfma_f32_16x16x32_bf16 v[116:119], v[144:147], v[204:207], v[116:119]
	v_mfma_f32_16x16x32_bf16 v[112:115], v[136:139], v[212:215], v[112:115]
	v_mfma_f32_16x16x32_bf16 v[108:111], v[144:147], v[212:215], v[108:111]
	v_mfma_f32_16x16x32_bf16 v[104:107], v[136:139], v[220:223], v[104:107]
	v_mfma_f32_16x16x32_bf16 v[100:103], v[144:147], v[220:223], v[100:103]
	v_mfma_f32_16x16x32_bf16 v[128:131], v[140:143], v[192:195], v[128:131]
	v_mfma_f32_16x16x32_bf16 v[124:127], v[148:151], v[192:195], v[124:127]
	v_mfma_f32_16x16x32_bf16 v[120:123], v[140:143], v[208:211], v[120:123]
	v_mfma_f32_16x16x32_bf16 v[116:119], v[148:151], v[208:211], v[116:119]
	v_mfma_f32_16x16x32_bf16 v[112:115], v[140:143], v[216:219], v[112:115]
	v_mfma_f32_16x16x32_bf16 v[108:111], v[148:151], v[216:219], v[108:111]
	v_mfma_f32_16x16x32_bf16 v[104:107], v[140:143], v[224:227], v[104:107]
	v_mfma_f32_16x16x32_bf16 v[100:103], v[148:151], v[224:227], v[100:103]
	s_setprio 0
	s_setprio 1
	v_mfma_f32_16x16x32_bf16 v[96:99], v[152:155], v[182:185], v[96:99]
	v_mfma_f32_16x16x32_bf16 v[92:95], v[174:177], v[182:185], v[92:95]
	v_mfma_f32_16x16x32_bf16 v[88:91], v[152:155], v[204:207], v[88:91]
	v_mfma_f32_16x16x32_bf16 v[84:87], v[174:177], v[204:207], v[84:87]
	v_mfma_f32_16x16x32_bf16 v[80:83], v[152:155], v[212:215], v[80:83]
	v_mfma_f32_16x16x32_bf16 v[76:79], v[174:177], v[212:215], v[76:79]
	v_mfma_f32_16x16x32_bf16 v[72:75], v[152:155], v[220:223], v[72:75]
	v_mfma_f32_16x16x32_bf16 v[68:71], v[174:177], v[220:223], v[68:71]
	v_mfma_f32_16x16x32_bf16 v[96:99], v[170:173], v[192:195], v[96:99]
	v_mfma_f32_16x16x32_bf16 v[92:95], v[178:181], v[192:195], v[92:95]
	v_mfma_f32_16x16x32_bf16 v[88:91], v[170:173], v[208:211], v[88:91]
	v_mfma_f32_16x16x32_bf16 v[84:87], v[178:181], v[208:211], v[84:87]
	v_mfma_f32_16x16x32_bf16 v[80:83], v[170:173], v[216:219], v[80:83]
	v_mfma_f32_16x16x32_bf16 v[76:79], v[178:181], v[216:219], v[76:79]
	v_mfma_f32_16x16x32_bf16 v[72:75], v[170:173], v[224:227], v[72:75]
	v_mfma_f32_16x16x32_bf16 v[68:71], v[178:181], v[224:227], v[68:71]
	s_barrier
	s_setprio 0
	s_add_i32 s74, s75, s47
	v_lshl_add_u64 v[186:187], s[24:25], 0, v[2:3]
	s_mov_b32 m0, s74
	ds_read_b128 v[182:185], v191 offset:16384
	ds_read_b128 v[192:195], v191 offset:17408
	ds_read_b128 v[204:207], v191 offset:18432
	ds_read_b128 v[208:211], v191 offset:19456
	ds_read_b128 v[212:215], v191 offset:20480
	ds_read_b128 v[216:219], v191 offset:21504
	ds_read_b128 v[220:223], v191 offset:22528
	ds_read_b128 v[224:227], v191 offset:23552
	global_load_lds_dwordx4 v[186:187], off
	s_add_i32 m0, s74, 0x2000
	s_add_u32 s74, s24, 0x80000
	v_lshl_add_u64 v[196:197], s[24:25], 0, v[156:157]
	s_addc_u32 s75, s25, 0
	s_add_i32 s67, s67, s47
	global_load_lds_dwordx4 v[196:197], off
	v_lshl_add_u64 v[228:229], s[74:75], 0, v[2:3]
	s_mov_b32 m0, s67
	v_lshl_add_u64 v[230:231], s[30:31], 0, v[158:159]
	global_load_lds_dwordx4 v[228:229], off
	v_lshl_add_u64 v[228:229], s[74:75], 0, v[156:157]
	s_add_i32 m0, s67, 0x2000
	s_nop 0
	global_load_lds_dwordx4 v[228:229], off
	v_lshl_add_u64 v[228:229], s[30:31], 0, v[160:161]
	s_mov_b32 m0, s48
	s_nop 0
	global_load_lds_dwordx4 v[228:229], off
	s_mov_b32 m0, s49
	s_nop 0
	global_load_lds_dwordx4 v[230:231], off
	s_waitcnt vmcnt(8)
	s_waitcnt lgkmcnt(0)
	s_barrier
	s_setprio 1
	s_waitcnt lgkmcnt(0)
	v_mfma_f32_16x16x32_bf16 v[64:67], v[136:139], v[182:185], v[64:67]
	v_mfma_f32_16x16x32_bf16 v[60:63], v[144:147], v[182:185], v[60:63]
	v_mfma_f32_16x16x32_bf16 v[56:59], v[136:139], v[204:207], v[56:59]
	v_mfma_f32_16x16x32_bf16 v[52:55], v[144:147], v[204:207], v[52:55]
	v_mfma_f32_16x16x32_bf16 v[48:51], v[136:139], v[212:215], v[48:51]
	v_mfma_f32_16x16x32_bf16 v[44:47], v[144:147], v[212:215], v[44:47]
	v_mfma_f32_16x16x32_bf16 v[40:43], v[136:139], v[220:223], v[40:43]
	v_mfma_f32_16x16x32_bf16 v[36:39], v[144:147], v[220:223], v[36:39]
	v_mfma_f32_16x16x32_bf16 v[64:67], v[140:143], v[192:195], v[64:67]
	v_mfma_f32_16x16x32_bf16 v[60:63], v[148:151], v[192:195], v[60:63]
	v_mfma_f32_16x16x32_bf16 v[56:59], v[140:143], v[208:211], v[56:59]
	v_mfma_f32_16x16x32_bf16 v[52:55], v[148:151], v[208:211], v[52:55]
	v_mfma_f32_16x16x32_bf16 v[48:51], v[140:143], v[216:219], v[48:51]
	v_mfma_f32_16x16x32_bf16 v[44:47], v[148:151], v[216:219], v[44:47]
	v_mfma_f32_16x16x32_bf16 v[40:43], v[140:143], v[224:227], v[40:43]
	v_mfma_f32_16x16x32_bf16 v[36:39], v[148:151], v[224:227], v[36:39]
	s_setprio 0
	s_setprio 1
	v_mfma_f32_16x16x32_bf16 v[32:35], v[152:155], v[182:185], v[32:35]
	v_mfma_f32_16x16x32_bf16 v[28:31], v[174:177], v[182:185], v[28:31]
	v_mfma_f32_16x16x32_bf16 v[24:27], v[152:155], v[204:207], v[24:27]
	v_mfma_f32_16x16x32_bf16 v[20:23], v[174:177], v[204:207], v[20:23]
	v_mfma_f32_16x16x32_bf16 v[16:19], v[152:155], v[212:215], v[16:19]
	v_mfma_f32_16x16x32_bf16 v[12:15], v[174:177], v[212:215], v[12:15]
	v_mfma_f32_16x16x32_bf16 v[8:11], v[152:155], v[220:223], v[8:11]
	v_mfma_f32_16x16x32_bf16 v[4:7], v[174:177], v[220:223], v[4:7]
	v_mfma_f32_16x16x32_bf16 v[32:35], v[170:173], v[192:195], v[32:35]
	v_mfma_f32_16x16x32_bf16 v[28:31], v[178:181], v[192:195], v[28:31]
	v_mfma_f32_16x16x32_bf16 v[24:27], v[170:173], v[208:211], v[24:27]
	v_mfma_f32_16x16x32_bf16 v[20:23], v[178:181], v[208:211], v[20:23]
	v_mfma_f32_16x16x32_bf16 v[16:19], v[170:173], v[216:219], v[16:19]
	v_mfma_f32_16x16x32_bf16 v[12:15], v[178:181], v[216:219], v[12:15]
	v_mfma_f32_16x16x32_bf16 v[8:11], v[170:173], v[224:227], v[8:11]
	v_mfma_f32_16x16x32_bf16 v[4:7], v[178:181], v[224:227], v[4:7]
	s_barrier
	s_setprio 0
	s_add_i32 s67, 0, 0x18000
	s_add_i32 s74, 0, 0x1c000
	v_add_u32_e32 v148, s67, v189
	v_add_u32_e32 v178, s74, v189
	ds_read_b128 v[136:139], v148
	ds_read_b128 v[140:143], v148 offset:1024
	ds_read_b128 v[144:147], v148 offset:2048
	ds_read_b128 v[148:151], v148 offset:3072
	ds_read_b128 v[152:155], v178
	ds_read_b128 v[170:173], v178 offset:1024
	ds_read_b128 v[174:177], v178 offset:2048
	ds_read_b128 v[178:181], v178 offset:3072
	s_add_u32 s30, s30, 0x80000
	s_addc_u32 s31, s31, 0
	s_mov_b32 m0, s50
	v_lshl_add_u64 v[232:233], s[30:31], 0, v[160:161]
	ds_read_b128 v[182:185], v191 offset:32768
	ds_read_b128 v[192:195], v191 offset:33792
	ds_read_b128 v[204:207], v191 offset:34816
	ds_read_b128 v[208:211], v191 offset:35840
	ds_read_b128 v[212:215], v191 offset:36864
	ds_read_b128 v[216:219], v191 offset:37888
	ds_read_b128 v[220:223], v191 offset:38912
	ds_read_b128 v[224:227], v191 offset:39936
	global_load_lds_dwordx4 v[232:233], off
	v_lshl_add_u64 v[232:233], s[30:31], 0, v[158:159]
	s_mov_b32 m0, s51
	s_nop 0
	global_load_lds_dwordx4 v[232:233], off
	s_waitcnt vmcnt(8)
	s_waitcnt lgkmcnt(0)
	s_barrier
	s_setprio 1
	s_waitcnt lgkmcnt(0)
	v_mfma_f32_16x16x32_bf16 v[128:131], v[136:139], v[182:185], v[128:131]
	v_mfma_f32_16x16x32_bf16 v[124:127], v[144:147], v[182:185], v[124:127]
	v_mfma_f32_16x16x32_bf16 v[120:123], v[136:139], v[204:207], v[120:123]
	v_mfma_f32_16x16x32_bf16 v[116:119], v[144:147], v[204:207], v[116:119]
	v_mfma_f32_16x16x32_bf16 v[112:115], v[136:139], v[212:215], v[112:115]
	v_mfma_f32_16x16x32_bf16 v[108:111], v[144:147], v[212:215], v[108:111]
	v_mfma_f32_16x16x32_bf16 v[104:107], v[136:139], v[220:223], v[104:107]
	v_mfma_f32_16x16x32_bf16 v[100:103], v[144:147], v[220:223], v[100:103]
	v_mfma_f32_16x16x32_bf16 v[128:131], v[140:143], v[192:195], v[128:131]
	v_mfma_f32_16x16x32_bf16 v[124:127], v[148:151], v[192:195], v[124:127]
	v_mfma_f32_16x16x32_bf16 v[120:123], v[140:143], v[208:211], v[120:123]
	v_mfma_f32_16x16x32_bf16 v[116:119], v[148:151], v[208:211], v[116:119]
	v_mfma_f32_16x16x32_bf16 v[112:115], v[140:143], v[216:219], v[112:115]
	v_mfma_f32_16x16x32_bf16 v[108:111], v[148:151], v[216:219], v[108:111]
	v_mfma_f32_16x16x32_bf16 v[104:107], v[140:143], v[224:227], v[104:107]
	v_mfma_f32_16x16x32_bf16 v[100:103], v[148:151], v[224:227], v[100:103]
	s_setprio 0
	s_setprio 1
	v_mfma_f32_16x16x32_bf16 v[96:99], v[152:155], v[182:185], v[96:99]
	v_mfma_f32_16x16x32_bf16 v[92:95], v[174:177], v[182:185], v[92:95]
	v_mfma_f32_16x16x32_bf16 v[88:91], v[152:155], v[204:207], v[88:91]
	v_mfma_f32_16x16x32_bf16 v[84:87], v[174:177], v[204:207], v[84:87]
	v_mfma_f32_16x16x32_bf16 v[80:83], v[152:155], v[212:215], v[80:83]
	v_mfma_f32_16x16x32_bf16 v[76:79], v[174:177], v[212:215], v[76:79]
	v_mfma_f32_16x16x32_bf16 v[72:75], v[152:155], v[220:223], v[72:75]
	v_mfma_f32_16x16x32_bf16 v[68:71], v[174:177], v[220:223], v[68:71]
	v_mfma_f32_16x16x32_bf16 v[96:99], v[170:173], v[192:195], v[96:99]
	v_mfma_f32_16x16x32_bf16 v[92:95], v[178:181], v[192:195], v[92:95]
	v_mfma_f32_16x16x32_bf16 v[88:91], v[170:173], v[208:211], v[88:91]
	v_mfma_f32_16x16x32_bf16 v[84:87], v[178:181], v[208:211], v[84:87]
	v_mfma_f32_16x16x32_bf16 v[80:83], v[170:173], v[216:219], v[80:83]
	v_mfma_f32_16x16x32_bf16 v[76:79], v[178:181], v[216:219], v[76:79]
	v_mfma_f32_16x16x32_bf16 v[72:75], v[170:173], v[224:227], v[72:75]
	v_mfma_f32_16x16x32_bf16 v[68:71], v[178:181], v[224:227], v[68:71]
	s_barrier
	s_setprio 0
	s_add_i32 s30, s67, s47
	v_lshl_add_u64 v[186:187], v[186:187], 0, s[28:29]
	s_mov_b32 m0, s30
	ds_read_b128 v[182:185], v191 offset:49152
	ds_read_b128 v[192:195], v191 offset:50176
	ds_read_b128 v[204:207], v191 offset:51200
	ds_read_b128 v[208:211], v191 offset:52224
	ds_read_b128 v[212:215], v191 offset:53248
	ds_read_b128 v[216:219], v191 offset:54272
	ds_read_b128 v[220:223], v191 offset:55296
	ds_read_b128 v[224:227], v191 offset:56320
	global_load_lds_dwordx4 v[186:187], off
	s_add_i32 m0, s30, 0x2000
	s_add_u32 s24, s24, 0x80080
	v_lshl_add_u64 v[186:187], v[196:197], 0, s[28:29]
	s_addc_u32 s25, s25, 0
	s_add_i32 s30, s74, s47
	global_load_lds_dwordx4 v[186:187], off
	v_lshl_add_u64 v[186:187], s[24:25], 0, v[2:3]
	s_mov_b32 m0, s30
	s_nop 0
	global_load_lds_dwordx4 v[186:187], off
	v_lshl_add_u64 v[186:187], s[24:25], 0, v[156:157]
	s_add_i32 m0, s30, 0x2000
	s_nop 0
	global_load_lds_dwordx4 v[186:187], off
	v_lshl_add_u64 v[186:187], v[228:229], 0, s[28:29]
	s_mov_b32 m0, s52
	s_nop 0
	global_load_lds_dwordx4 v[186:187], off
	v_lshl_add_u64 v[186:187], v[230:231], 0, s[28:29]
	s_mov_b32 m0, s53
	s_nop 0
	global_load_lds_dwordx4 v[186:187], off
	s_waitcnt vmcnt(8)
	s_waitcnt lgkmcnt(0)
	s_barrier
	s_setprio 1
	s_waitcnt lgkmcnt(0)
	v_mfma_f32_16x16x32_bf16 v[64:67], v[136:139], v[182:185], v[64:67]
	v_mfma_f32_16x16x32_bf16 v[60:63], v[144:147], v[182:185], v[60:63]
	v_mfma_f32_16x16x32_bf16 v[56:59], v[136:139], v[204:207], v[56:59]
	v_mfma_f32_16x16x32_bf16 v[52:55], v[144:147], v[204:207], v[52:55]
	v_mfma_f32_16x16x32_bf16 v[48:51], v[136:139], v[212:215], v[48:51]
	v_mfma_f32_16x16x32_bf16 v[44:47], v[144:147], v[212:215], v[44:47]
	v_mfma_f32_16x16x32_bf16 v[40:43], v[136:139], v[220:223], v[40:43]
	v_mfma_f32_16x16x32_bf16 v[36:39], v[144:147], v[220:223], v[36:39]
	v_mfma_f32_16x16x32_bf16 v[64:67], v[140:143], v[192:195], v[64:67]
	v_mfma_f32_16x16x32_bf16 v[60:63], v[148:151], v[192:195], v[60:63]
	v_mfma_f32_16x16x32_bf16 v[56:59], v[140:143], v[208:211], v[56:59]
	v_mfma_f32_16x16x32_bf16 v[52:55], v[148:151], v[208:211], v[52:55]
	v_mfma_f32_16x16x32_bf16 v[48:51], v[140:143], v[216:219], v[48:51]
	v_mfma_f32_16x16x32_bf16 v[44:47], v[148:151], v[216:219], v[44:47]
	v_mfma_f32_16x16x32_bf16 v[40:43], v[140:143], v[224:227], v[40:43]
	v_mfma_f32_16x16x32_bf16 v[36:39], v[148:151], v[224:227], v[36:39]
	s_setprio 0
	s_setprio 1
	v_mfma_f32_16x16x32_bf16 v[32:35], v[152:155], v[182:185], v[32:35]
	v_mfma_f32_16x16x32_bf16 v[28:31], v[174:177], v[182:185], v[28:31]
	v_mfma_f32_16x16x32_bf16 v[24:27], v[152:155], v[204:207], v[24:27]
	v_mfma_f32_16x16x32_bf16 v[20:23], v[174:177], v[204:207], v[20:23]
	v_mfma_f32_16x16x32_bf16 v[16:19], v[152:155], v[212:215], v[16:19]
	v_mfma_f32_16x16x32_bf16 v[12:15], v[174:177], v[212:215], v[12:15]
	v_mfma_f32_16x16x32_bf16 v[8:11], v[152:155], v[220:223], v[8:11]
	v_mfma_f32_16x16x32_bf16 v[4:7], v[174:177], v[220:223], v[4:7]
	v_mfma_f32_16x16x32_bf16 v[32:35], v[170:173], v[192:195], v[32:35]
	v_mfma_f32_16x16x32_bf16 v[28:31], v[178:181], v[192:195], v[28:31]
	v_mfma_f32_16x16x32_bf16 v[24:27], v[170:173], v[208:211], v[24:27]
	v_mfma_f32_16x16x32_bf16 v[20:23], v[178:181], v[208:211], v[20:23]
	v_mfma_f32_16x16x32_bf16 v[16:19], v[170:173], v[216:219], v[16:19]
	v_mfma_f32_16x16x32_bf16 v[12:15], v[178:181], v[216:219], v[12:15]
	v_mfma_f32_16x16x32_bf16 v[8:11], v[170:173], v[224:227], v[8:11]
	v_mfma_f32_16x16x32_bf16 v[4:7], v[178:181], v[224:227], v[4:7]
	s_barrier
	s_setprio 0
	s_add_i32 s66, s66, 2
	s_add_u32 s10, s10, 0x100
	s_addc_u32 s11, s11, 0
	s_cmp_gt_u32 s66, 29
	s_cbranch_scc0 .LBB0_866
	s_and_b64 vcc, exec, s[12:13]
	s_cbranch_vccz .LBB0_869
	s_barrier
